# LDS-DMA 2-stage software-pipelined main loop rolled out to gemm_in, gateup, resid-out, resid-down, cmp1 sites
# speedup vs baseline: 1.1202x; 1.0827x over previous
.LBB0_49:
	v_lshrrev_b32_e32 v2, 6, v134
	v_lshlrev_b32_e32 v3, 4, v134
	v_bfe_u32 v0, v134, 3, 3
	v_and_b32_e32 v3, 0x70, v3
	v_and_b32_e32 v4, 8, v2
	v_or3_b32 v135, v3, v4, v0
	v_ashrrev_i32_e32 v0, 7, v134
	v_bfi_b32 v136, -8, v0, v2
	v_mul_u32_u24_e32 v0, 0x5a000, v135
	v_mov_b64_e32 v[2:3], s[58:59]
	s_mov_b32 s2, 0xb4000
	v_lshlrev_b32_e32 v0, 1, v0
	v_mad_i64_i32 v[6:7], s[2:3], v136, s2, v[2:3]
	v_mov_b32_e32 v2, v163
	v_lshl_add_u64 v[4:5], s[78:79], 0, v[0:1]
	s_nop 0
	v_ashrrev_i32_e32 v3, 3, v2
	v_lshlrev_b32_e32 v0, 4, v2
	v_mad_i64_i32 v[4:5], s[2:3], v3, s38, v[4:5]
	v_and_b32_e32 v0, 0x70, v0
	v_lshl_add_u64 v[130:131], v[4:5], 0, v[0:1]
	v_add_co_u32_e32 v32, vcc, s39, v130
	v_mad_i64_i32 v[4:5], s[2:3], v3, s38, v[6:7]
	v_lshl_add_u64 v[132:133], v[4:5], 0, v[0:1]
	v_and_b32_e32 v110, 7, v163
	v_bfe_u32 v111, v163, 4, 3
	v_xor_b32_e32 v111, v111, v110
	v_sub_u32_e32 v111, v111, v110
	v_lshlrev_b32_e32 v111, 4, v111
	v_lshrrev_b32_e32 v112, 6, v163
	v_lshlrev_b32_e32 v112, 10, v112
	v_readfirstlane_b32 s2, v130
	v_readfirstlane_b32 s3, v131
	v_readfirstlane_b32 s4, v132
	v_readfirstlane_b32 s5, v133
	v_readfirstlane_b32 s6, v112
	s_nop 3
	v_subrev_u32_e32 v98, s2, v130
	v_subrev_u32_e32 v102, s4, v132
	v_add_u32_e32 v98, v98, v111
	v_add_u32_e32 v102, v102, v111
	v_add_u32_e32 v99, 0x2d000, v98
	v_add_u32_e32 v103, 0x2d000, v102
	v_add_u32_e32 v100, 0x5a000, v98
	v_add_u32_e32 v104, 0x5a000, v102
	v_add_u32_e32 v101, 0x87000, v98
	v_add_u32_e32 v105, 0x87000, v102
	v_lshlrev_b32_e32 v110, 3, v163
	v_lshlrev_b32_e32 v111, 7, v163
	v_and_b32_e32 v112, 0x2000, v111
	v_and_b32_e32 v111, 0x780, v111
	v_and_b32_e32 v107, 64, v110
	v_xor_b32_e32 v110, v110, v163
	v_and_b32_e32 v110, 48, v110
	v_or3_b32 v110, v111, v107, v110
	v_lshlrev_b32_e32 v111, 6, v163
	v_and_b32_e32 v111, 0xffffe000, v111
	v_or_b32_e32 v108, v110, v112
	v_or_b32_e32 v106, v110, v111
	v_xor_b32_e32 v107, 64, v106
	v_xor_b32_e32 v109, 64, v108
	s_mov_b32 m0, s6
	s_nop 0
	global_load_lds_dwordx4 v98, s[2:3]
	s_add_u32 m0, s6, 0x1000
	s_nop 0
	global_load_lds_dwordx4 v99, s[2:3]
	s_add_u32 m0, s6, 0x2000
	s_nop 0
	global_load_lds_dwordx4 v100, s[2:3]
	s_add_u32 m0, s6, 0x3000
	s_nop 0
	global_load_lds_dwordx4 v101, s[2:3]
	s_add_u32 m0, s6, 0x4000
	s_nop 0
	global_load_lds_dwordx4 v102, s[4:5]
	s_add_u32 m0, s6, 0x5000
	s_nop 0
	global_load_lds_dwordx4 v103, s[4:5]
	s_add_u32 m0, s6, 0x6000
	s_nop 0
	global_load_lds_dwordx4 v104, s[4:5]
	s_add_u32 m0, s6, 0x7000
	s_nop 0
	global_load_lds_dwordx4 v105, s[4:5]
	s_add_u32 s2, s2, 0x80
	s_addc_u32 s3, s3, 0
	s_add_u32 s4, s4, 0x80
	s_addc_u32 s5, s5, 0
	s_waitcnt vmcnt(0)
	s_barrier
	s_add_u32 m0, s6, 0x8000
	ds_read_b128 v[142:145], v106
	ds_read_b128 v[158:161], v108 offset:16384
	s_nop 0
	global_load_lds_dwordx4 v98, s[2:3]
	s_add_u32 m0, s6, 0x9000
	ds_read_b128 v[182:185], v108 offset:18432
	ds_read_b128 v[186:189], v108 offset:20480
	s_nop 0
	global_load_lds_dwordx4 v99, s[2:3]
	s_add_u32 m0, s6, 0xa000
	ds_read_b128 v[206:209], v108 offset:22528
	ds_read_b128 v[146:149], v106 offset:2048
	s_nop 0
	global_load_lds_dwordx4 v100, s[2:3]
	s_add_u32 m0, s6, 0xb000
	ds_read_b128 v[150:153], v106 offset:4096
	ds_read_b128 v[154:157], v106 offset:6144
	s_nop 0
	global_load_lds_dwordx4 v101, s[2:3]
	s_add_u32 m0, s6, 0xc000
	s_nop 0
	global_load_lds_dwordx4 v102, s[4:5]
	s_add_u32 m0, s6, 0xd000
	s_nop 0
	global_load_lds_dwordx4 v103, s[4:5]
	s_add_u32 m0, s6, 0xe000
	s_nop 0
	global_load_lds_dwordx4 v104, s[4:5]
	s_add_u32 m0, s6, 0xf000
	s_nop 0
	global_load_lds_dwordx4 v105, s[4:5]
	s_add_u32 s2, s2, 0x80
	s_addc_u32 s3, s3, 0
	s_add_u32 s4, s4, 0x80
	s_addc_u32 s5, s5, 0
	s_waitcnt lgkmcnt(0)
	v_mfma_f32_16x16x32_bf16 v[94:97], v[158:161], v[142:145], 0
	ds_read_b128 v[34:37], v107
	ds_read_b128 v[54:57], v109 offset:16384
	v_mfma_f32_16x16x32_bf16 v[90:93], v[182:185], v[142:145], 0
	v_mfma_f32_16x16x32_bf16 v[86:89], v[186:189], v[142:145], 0
	ds_read_b128 v[62:65], v109 offset:18432
	ds_read_b128 v[66:69], v109 offset:20480
	v_mfma_f32_16x16x32_bf16 v[82:85], v[206:209], v[142:145], 0
	v_mfma_f32_16x16x32_bf16 v[74:77], v[158:161], v[146:149], 0
	ds_read_b128 v[78:81], v109 offset:22528
	ds_read_b128 v[38:41], v107 offset:2048
	v_mfma_f32_16x16x32_bf16 v[70:73], v[182:185], v[146:149], 0
	v_mfma_f32_16x16x32_bf16 v[58:61], v[186:189], v[146:149], 0
	ds_read_b128 v[46:49], v107 offset:4096
	ds_read_b128 v[50:53], v107 offset:6144
	v_mfma_f32_16x16x32_bf16 v[42:45], v[206:209], v[146:149], 0
	v_mfma_f32_16x16x32_bf16 v[30:33], v[158:161], v[150:153], 0
	v_mfma_f32_16x16x32_bf16 v[26:29], v[182:185], v[150:153], 0
	v_mfma_f32_16x16x32_bf16 v[22:25], v[186:189], v[150:153], 0
	v_mfma_f32_16x16x32_bf16 v[18:21], v[206:209], v[150:153], 0
	v_mfma_f32_16x16x32_bf16 v[14:17], v[158:161], v[154:157], 0
	v_mfma_f32_16x16x32_bf16 v[10:13], v[182:185], v[154:157], 0
	v_mfma_f32_16x16x32_bf16 v[6:9], v[186:189], v[154:157], 0
	v_mfma_f32_16x16x32_bf16 v[2:5], v[206:209], v[154:157], 0
	s_waitcnt vmcnt(0) lgkmcnt(0)
	s_barrier
	s_movk_i32 s7, 21
.Lg10_loop:
	v_mfma_f32_16x16x32_bf16 v[94:97], v[54:57], v[34:37], v[94:97]
	s_mov_b32 m0, s6
	ds_read_b128 v[142:145], v106 offset:32768
	ds_read_b128 v[158:161], v108 offset:49152
	v_mfma_f32_16x16x32_bf16 v[90:93], v[62:65], v[34:37], v[90:93]
	global_load_lds_dwordx4 v98, s[2:3]
	v_mfma_f32_16x16x32_bf16 v[86:89], v[66:69], v[34:37], v[86:89]
	s_add_u32 m0, s6, 0x1000
	ds_read_b128 v[182:185], v108 offset:51200
	ds_read_b128 v[186:189], v108 offset:53248
	v_mfma_f32_16x16x32_bf16 v[82:85], v[78:81], v[34:37], v[82:85]
	global_load_lds_dwordx4 v99, s[2:3]
	v_mfma_f32_16x16x32_bf16 v[74:77], v[54:57], v[38:41], v[74:77]
	s_add_u32 m0, s6, 0x2000
	ds_read_b128 v[206:209], v108 offset:55296
	ds_read_b128 v[146:149], v106 offset:34816
	v_mfma_f32_16x16x32_bf16 v[70:73], v[62:65], v[38:41], v[70:73]
	global_load_lds_dwordx4 v100, s[2:3]
	v_mfma_f32_16x16x32_bf16 v[58:61], v[66:69], v[38:41], v[58:61]
	s_add_u32 m0, s6, 0x3000
	ds_read_b128 v[150:153], v106 offset:36864
	ds_read_b128 v[154:157], v106 offset:38912
	v_mfma_f32_16x16x32_bf16 v[42:45], v[78:81], v[38:41], v[42:45]
	global_load_lds_dwordx4 v101, s[2:3]
	v_mfma_f32_16x16x32_bf16 v[30:33], v[54:57], v[46:49], v[30:33]
	s_add_u32 m0, s6, 0x4000
	v_mfma_f32_16x16x32_bf16 v[26:29], v[62:65], v[46:49], v[26:29]
	global_load_lds_dwordx4 v102, s[4:5]
	v_mfma_f32_16x16x32_bf16 v[22:25], v[66:69], v[46:49], v[22:25]
	s_add_u32 m0, s6, 0x5000
	v_mfma_f32_16x16x32_bf16 v[18:21], v[78:81], v[46:49], v[18:21]
	global_load_lds_dwordx4 v103, s[4:5]
	v_mfma_f32_16x16x32_bf16 v[14:17], v[54:57], v[50:53], v[14:17]
	s_add_u32 m0, s6, 0x6000
	v_mfma_f32_16x16x32_bf16 v[10:13], v[62:65], v[50:53], v[10:13]
	global_load_lds_dwordx4 v104, s[4:5]
	v_mfma_f32_16x16x32_bf16 v[6:9], v[66:69], v[50:53], v[6:9]
	s_add_u32 m0, s6, 0x7000
	v_mfma_f32_16x16x32_bf16 v[2:5], v[78:81], v[50:53], v[2:5]
	global_load_lds_dwordx4 v105, s[4:5]
	s_add_u32 s2, s2, 0x80
	s_addc_u32 s3, s3, 0
	s_add_u32 s4, s4, 0x80
	s_addc_u32 s5, s5, 0
	s_waitcnt lgkmcnt(0)
	v_mfma_f32_16x16x32_bf16 v[94:97], v[158:161], v[142:145], v[94:97]
	ds_read_b128 v[34:37], v107 offset:32768
	ds_read_b128 v[54:57], v109 offset:49152
	v_mfma_f32_16x16x32_bf16 v[90:93], v[182:185], v[142:145], v[90:93]
	v_mfma_f32_16x16x32_bf16 v[86:89], v[186:189], v[142:145], v[86:89]
	ds_read_b128 v[62:65], v109 offset:51200
	ds_read_b128 v[66:69], v109 offset:53248
	v_mfma_f32_16x16x32_bf16 v[82:85], v[206:209], v[142:145], v[82:85]
	v_mfma_f32_16x16x32_bf16 v[74:77], v[158:161], v[146:149], v[74:77]
	ds_read_b128 v[78:81], v109 offset:55296
	ds_read_b128 v[38:41], v107 offset:34816
	v_mfma_f32_16x16x32_bf16 v[70:73], v[182:185], v[146:149], v[70:73]
	v_mfma_f32_16x16x32_bf16 v[58:61], v[186:189], v[146:149], v[58:61]
	ds_read_b128 v[46:49], v107 offset:36864
	ds_read_b128 v[50:53], v107 offset:38912
	v_mfma_f32_16x16x32_bf16 v[42:45], v[206:209], v[146:149], v[42:45]
	v_mfma_f32_16x16x32_bf16 v[30:33], v[158:161], v[150:153], v[30:33]
	v_mfma_f32_16x16x32_bf16 v[26:29], v[182:185], v[150:153], v[26:29]
	v_mfma_f32_16x16x32_bf16 v[22:25], v[186:189], v[150:153], v[22:25]
	v_mfma_f32_16x16x32_bf16 v[18:21], v[206:209], v[150:153], v[18:21]
	v_mfma_f32_16x16x32_bf16 v[14:17], v[158:161], v[154:157], v[14:17]
	v_mfma_f32_16x16x32_bf16 v[10:13], v[182:185], v[154:157], v[10:13]
	v_mfma_f32_16x16x32_bf16 v[6:9], v[186:189], v[154:157], v[6:9]
	v_mfma_f32_16x16x32_bf16 v[2:5], v[206:209], v[154:157], v[2:5]
	s_waitcnt vmcnt(0) lgkmcnt(0)
	s_barrier
	v_mfma_f32_16x16x32_bf16 v[94:97], v[54:57], v[34:37], v[94:97]
	s_add_u32 m0, s6, 0x8000
	ds_read_b128 v[142:145], v106
	ds_read_b128 v[158:161], v108 offset:16384
	v_mfma_f32_16x16x32_bf16 v[90:93], v[62:65], v[34:37], v[90:93]
	global_load_lds_dwordx4 v98, s[2:3]
	v_mfma_f32_16x16x32_bf16 v[86:89], v[66:69], v[34:37], v[86:89]
	s_add_u32 m0, s6, 0x9000
	ds_read_b128 v[182:185], v108 offset:18432
	ds_read_b128 v[186:189], v108 offset:20480
	v_mfma_f32_16x16x32_bf16 v[82:85], v[78:81], v[34:37], v[82:85]
	global_load_lds_dwordx4 v99, s[2:3]
	v_mfma_f32_16x16x32_bf16 v[74:77], v[54:57], v[38:41], v[74:77]
	s_add_u32 m0, s6, 0xa000
	ds_read_b128 v[206:209], v108 offset:22528
	ds_read_b128 v[146:149], v106 offset:2048
	v_mfma_f32_16x16x32_bf16 v[70:73], v[62:65], v[38:41], v[70:73]
	global_load_lds_dwordx4 v100, s[2:3]
	v_mfma_f32_16x16x32_bf16 v[58:61], v[66:69], v[38:41], v[58:61]
	s_add_u32 m0, s6, 0xb000
	ds_read_b128 v[150:153], v106 offset:4096
	ds_read_b128 v[154:157], v106 offset:6144
	v_mfma_f32_16x16x32_bf16 v[42:45], v[78:81], v[38:41], v[42:45]
	global_load_lds_dwordx4 v101, s[2:3]
	v_mfma_f32_16x16x32_bf16 v[30:33], v[54:57], v[46:49], v[30:33]
	s_add_u32 m0, s6, 0xc000
	v_mfma_f32_16x16x32_bf16 v[26:29], v[62:65], v[46:49], v[26:29]
	global_load_lds_dwordx4 v102, s[4:5]
	v_mfma_f32_16x16x32_bf16 v[22:25], v[66:69], v[46:49], v[22:25]
	s_add_u32 m0, s6, 0xd000
	v_mfma_f32_16x16x32_bf16 v[18:21], v[78:81], v[46:49], v[18:21]
	global_load_lds_dwordx4 v103, s[4:5]
	v_mfma_f32_16x16x32_bf16 v[14:17], v[54:57], v[50:53], v[14:17]
	s_add_u32 m0, s6, 0xe000
	v_mfma_f32_16x16x32_bf16 v[10:13], v[62:65], v[50:53], v[10:13]
	global_load_lds_dwordx4 v104, s[4:5]
	v_mfma_f32_16x16x32_bf16 v[6:9], v[66:69], v[50:53], v[6:9]
	s_add_u32 m0, s6, 0xf000
	v_mfma_f32_16x16x32_bf16 v[2:5], v[78:81], v[50:53], v[2:5]
	global_load_lds_dwordx4 v105, s[4:5]
	s_add_u32 s2, s2, 0x80
	s_addc_u32 s3, s3, 0
	s_add_u32 s4, s4, 0x80
	s_addc_u32 s5, s5, 0
	s_waitcnt lgkmcnt(0)
	v_mfma_f32_16x16x32_bf16 v[94:97], v[158:161], v[142:145], v[94:97]
	ds_read_b128 v[34:37], v107
	ds_read_b128 v[54:57], v109 offset:16384
	v_mfma_f32_16x16x32_bf16 v[90:93], v[182:185], v[142:145], v[90:93]
	v_mfma_f32_16x16x32_bf16 v[86:89], v[186:189], v[142:145], v[86:89]
	ds_read_b128 v[62:65], v109 offset:18432
	ds_read_b128 v[66:69], v109 offset:20480
	v_mfma_f32_16x16x32_bf16 v[82:85], v[206:209], v[142:145], v[82:85]
	v_mfma_f32_16x16x32_bf16 v[74:77], v[158:161], v[146:149], v[74:77]
	ds_read_b128 v[78:81], v109 offset:22528
	ds_read_b128 v[38:41], v107 offset:2048
	v_mfma_f32_16x16x32_bf16 v[70:73], v[182:185], v[146:149], v[70:73]
	v_mfma_f32_16x16x32_bf16 v[58:61], v[186:189], v[146:149], v[58:61]
	ds_read_b128 v[46:49], v107 offset:4096
	ds_read_b128 v[50:53], v107 offset:6144
	v_mfma_f32_16x16x32_bf16 v[42:45], v[206:209], v[146:149], v[42:45]
	v_mfma_f32_16x16x32_bf16 v[30:33], v[158:161], v[150:153], v[30:33]
	v_mfma_f32_16x16x32_bf16 v[26:29], v[182:185], v[150:153], v[26:29]
	v_mfma_f32_16x16x32_bf16 v[22:25], v[186:189], v[150:153], v[22:25]
	v_mfma_f32_16x16x32_bf16 v[18:21], v[206:209], v[150:153], v[18:21]
	v_mfma_f32_16x16x32_bf16 v[14:17], v[158:161], v[154:157], v[14:17]
	v_mfma_f32_16x16x32_bf16 v[10:13], v[182:185], v[154:157], v[10:13]
	v_mfma_f32_16x16x32_bf16 v[6:9], v[186:189], v[154:157], v[6:9]
	v_mfma_f32_16x16x32_bf16 v[2:5], v[206:209], v[154:157], v[2:5]
	s_add_i32 s7, s7, -1
	s_waitcnt vmcnt(0) lgkmcnt(0)
	s_barrier
	s_cmp_lg_u32 s7, 0
	s_cbranch_scc1 .Lg10_loop
	v_mfma_f32_16x16x32_bf16 v[94:97], v[54:57], v[34:37], v[94:97]
	ds_read_b128 v[142:145], v106 offset:32768
	ds_read_b128 v[158:161], v108 offset:49152
	v_mfma_f32_16x16x32_bf16 v[90:93], v[62:65], v[34:37], v[90:93]
	v_mfma_f32_16x16x32_bf16 v[86:89], v[66:69], v[34:37], v[86:89]
	ds_read_b128 v[182:185], v108 offset:51200
	ds_read_b128 v[186:189], v108 offset:53248
	v_mfma_f32_16x16x32_bf16 v[82:85], v[78:81], v[34:37], v[82:85]
	v_mfma_f32_16x16x32_bf16 v[74:77], v[54:57], v[38:41], v[74:77]
	ds_read_b128 v[206:209], v108 offset:55296
	ds_read_b128 v[146:149], v106 offset:34816
	v_mfma_f32_16x16x32_bf16 v[70:73], v[62:65], v[38:41], v[70:73]
	v_mfma_f32_16x16x32_bf16 v[58:61], v[66:69], v[38:41], v[58:61]
	ds_read_b128 v[150:153], v106 offset:36864
	ds_read_b128 v[154:157], v106 offset:38912
	v_mfma_f32_16x16x32_bf16 v[42:45], v[78:81], v[38:41], v[42:45]
	v_mfma_f32_16x16x32_bf16 v[30:33], v[54:57], v[46:49], v[30:33]
	v_mfma_f32_16x16x32_bf16 v[26:29], v[62:65], v[46:49], v[26:29]
	v_mfma_f32_16x16x32_bf16 v[22:25], v[66:69], v[46:49], v[22:25]
	v_mfma_f32_16x16x32_bf16 v[18:21], v[78:81], v[46:49], v[18:21]
	v_mfma_f32_16x16x32_bf16 v[14:17], v[54:57], v[50:53], v[14:17]
	v_mfma_f32_16x16x32_bf16 v[10:13], v[62:65], v[50:53], v[10:13]
	v_mfma_f32_16x16x32_bf16 v[6:9], v[66:69], v[50:53], v[6:9]
	v_mfma_f32_16x16x32_bf16 v[2:5], v[78:81], v[50:53], v[2:5]
	s_waitcnt lgkmcnt(0)
	v_mfma_f32_16x16x32_bf16 v[94:97], v[158:161], v[142:145], v[94:97]
	ds_read_b128 v[34:37], v107 offset:32768
	ds_read_b128 v[54:57], v109 offset:49152
	v_mfma_f32_16x16x32_bf16 v[90:93], v[182:185], v[142:145], v[90:93]
	v_mfma_f32_16x16x32_bf16 v[86:89], v[186:189], v[142:145], v[86:89]
	ds_read_b128 v[62:65], v109 offset:51200
	ds_read_b128 v[66:69], v109 offset:53248
	v_mfma_f32_16x16x32_bf16 v[82:85], v[206:209], v[142:145], v[82:85]
	v_mfma_f32_16x16x32_bf16 v[74:77], v[158:161], v[146:149], v[74:77]
	ds_read_b128 v[78:81], v109 offset:55296
	ds_read_b128 v[38:41], v107 offset:34816
	v_mfma_f32_16x16x32_bf16 v[70:73], v[182:185], v[146:149], v[70:73]
	v_mfma_f32_16x16x32_bf16 v[58:61], v[186:189], v[146:149], v[58:61]
	ds_read_b128 v[46:49], v107 offset:36864
	ds_read_b128 v[50:53], v107 offset:38912
	v_mfma_f32_16x16x32_bf16 v[42:45], v[206:209], v[146:149], v[42:45]
	v_mfma_f32_16x16x32_bf16 v[30:33], v[158:161], v[150:153], v[30:33]
	v_mfma_f32_16x16x32_bf16 v[26:29], v[182:185], v[150:153], v[26:29]
	v_mfma_f32_16x16x32_bf16 v[22:25], v[186:189], v[150:153], v[22:25]
	v_mfma_f32_16x16x32_bf16 v[18:21], v[206:209], v[150:153], v[18:21]
	v_mfma_f32_16x16x32_bf16 v[14:17], v[158:161], v[154:157], v[14:17]
	v_mfma_f32_16x16x32_bf16 v[10:13], v[182:185], v[154:157], v[10:13]
	v_mfma_f32_16x16x32_bf16 v[6:9], v[186:189], v[154:157], v[6:9]
	v_mfma_f32_16x16x32_bf16 v[2:5], v[206:209], v[154:157], v[2:5]
	s_waitcnt lgkmcnt(0)
	s_barrier
	v_mfma_f32_16x16x32_bf16 v[94:97], v[54:57], v[34:37], v[94:97]
	v_mfma_f32_16x16x32_bf16 v[90:93], v[62:65], v[34:37], v[90:93]
	v_mfma_f32_16x16x32_bf16 v[86:89], v[66:69], v[34:37], v[86:89]
	v_mfma_f32_16x16x32_bf16 v[82:85], v[78:81], v[34:37], v[82:85]
	v_mfma_f32_16x16x32_bf16 v[74:77], v[54:57], v[38:41], v[74:77]
	v_mfma_f32_16x16x32_bf16 v[70:73], v[62:65], v[38:41], v[70:73]
	v_mfma_f32_16x16x32_bf16 v[58:61], v[66:69], v[38:41], v[58:61]
	v_mfma_f32_16x16x32_bf16 v[42:45], v[78:81], v[38:41], v[42:45]
	v_mfma_f32_16x16x32_bf16 v[30:33], v[54:57], v[46:49], v[30:33]
	v_mfma_f32_16x16x32_bf16 v[26:29], v[62:65], v[46:49], v[26:29]
	v_mfma_f32_16x16x32_bf16 v[22:25], v[66:69], v[46:49], v[22:25]
	v_mfma_f32_16x16x32_bf16 v[18:21], v[78:81], v[46:49], v[18:21]
	v_mfma_f32_16x16x32_bf16 v[14:17], v[54:57], v[50:53], v[14:17]
	v_mfma_f32_16x16x32_bf16 v[10:13], v[62:65], v[50:53], v[10:13]
	v_mfma_f32_16x16x32_bf16 v[6:9], v[66:69], v[50:53], v[6:9]
	v_mfma_f32_16x16x32_bf16 v[2:5], v[78:81], v[50:53], v[2:5]
	s_nop 7
	s_nop 2
	s_branch .LBB0_48

.LBB0_59:
	s_movk_i32 s2, 0x13ff
	v_and_b32_e32 v0, 7, v134
	v_cmp_lt_i32_e32 vcc, s2, v134
	s_and_saveexec_b64 s[2:3], vcc
	s_xor_b64 s[2:3], exec, s[2:3]
	v_add_u32_e32 v2, 0xffffec00, v134
	v_bfe_u32 v3, v134, 3, 4
	v_lshl_or_b32 v135, v0, 4, v3
	v_lshrrev_b32_e32 v0, 7, v2
	v_add_u32_e32 v136, 40, v0
	s_andn2_saveexec_b64 s[2:3], s[2:3]
	v_lshrrev_b32_e32 v3, 6, v134
	v_bfe_u32 v2, v134, 3, 3
	v_lshlrev_b32_e32 v0, 4, v0
	v_and_b32_e32 v4, 8, v3
	v_or3_b32 v135, v0, v4, v2
	v_ashrrev_i32_e32 v0, 7, v134
	v_bfi_b32 v136, -8, v0, v3
	s_or_b64 exec, exec, s[2:3]
	v_mov_b64_e32 v[2:3], s[80:81]
	s_mov_b32 s4, 0x44000
	v_mad_u64_u32 v[4:5], s[2:3], v135, s4, v[2:3]
	v_mov_b64_e32 v[2:3], s[56:57]
	v_mad_i64_i32 v[6:7], s[2:3], v136, s4, v[2:3]
	v_mov_b32_e32 v2, v163
	s_mov_b32 s4, 0x22000
	v_ashrrev_i32_e32 v3, 3, v2
	v_lshlrev_b32_e32 v0, 4, v2
	v_mad_i64_i32 v[4:5], s[2:3], v3, s43, v[4:5]
	v_and_b32_e32 v0, 0x70, v0
	v_lshl_add_u64 v[130:131], v[4:5], 0, v[0:1]
	v_mad_i64_i32 v[4:5], s[2:3], v3, s43, v[6:7]
	v_lshl_add_u64 v[132:133], v[4:5], 0, v[0:1]
	v_and_b32_e32 v110, 7, v163
	v_bfe_u32 v111, v163, 4, 3
	v_xor_b32_e32 v111, v111, v110
	v_sub_u32_e32 v111, v111, v110
	v_lshlrev_b32_e32 v111, 4, v111
	v_lshrrev_b32_e32 v112, 6, v163
	v_lshlrev_b32_e32 v112, 10, v112
	v_readfirstlane_b32 s2, v130
	v_readfirstlane_b32 s3, v131
	v_readfirstlane_b32 s4, v132
	v_readfirstlane_b32 s5, v133
	v_readfirstlane_b32 s6, v112
	s_nop 3
	v_subrev_u32_e32 v98, s2, v130
	v_subrev_u32_e32 v102, s4, v132
	v_add_u32_e32 v98, v98, v111
	v_add_u32_e32 v102, v102, v111
	v_add_u32_e32 v99, 0x11000, v98
	v_add_u32_e32 v103, 0x11000, v102
	v_add_u32_e32 v100, 0x22000, v98
	v_add_u32_e32 v104, 0x22000, v102
	v_add_u32_e32 v101, 0x33000, v98
	v_add_u32_e32 v105, 0x33000, v102
	v_lshlrev_b32_e32 v110, 3, v163
	v_lshlrev_b32_e32 v111, 7, v163
	v_and_b32_e32 v112, 0x2000, v111
	v_and_b32_e32 v111, 0x780, v111
	v_and_b32_e32 v107, 64, v110
	v_xor_b32_e32 v110, v110, v163
	v_and_b32_e32 v110, 48, v110
	v_or3_b32 v110, v111, v107, v110
	v_lshlrev_b32_e32 v111, 6, v163
	v_and_b32_e32 v111, 0xffffe000, v111
	v_or_b32_e32 v108, v110, v112
	v_or_b32_e32 v106, v110, v111
	v_xor_b32_e32 v107, 64, v106
	v_xor_b32_e32 v109, 64, v108
	s_mov_b32 m0, s6
	s_nop 0
	global_load_lds_dwordx4 v98, s[2:3]
	s_add_u32 m0, s6, 0x1000
	s_nop 0
	global_load_lds_dwordx4 v99, s[2:3]
	s_add_u32 m0, s6, 0x2000
	s_nop 0
	global_load_lds_dwordx4 v100, s[2:3]
	s_add_u32 m0, s6, 0x3000
	s_nop 0
	global_load_lds_dwordx4 v101, s[2:3]
	s_add_u32 m0, s6, 0x4000
	s_nop 0
	global_load_lds_dwordx4 v102, s[4:5]
	s_add_u32 m0, s6, 0x5000
	s_nop 0
	global_load_lds_dwordx4 v103, s[4:5]
	s_add_u32 m0, s6, 0x6000
	s_nop 0
	global_load_lds_dwordx4 v104, s[4:5]
	s_add_u32 m0, s6, 0x7000
	s_nop 0
	global_load_lds_dwordx4 v105, s[4:5]
	s_add_u32 s2, s2, 0x80
	s_addc_u32 s3, s3, 0
	s_add_u32 s4, s4, 0x80
	s_addc_u32 s5, s5, 0
	s_waitcnt vmcnt(0)
	s_barrier
	s_add_u32 m0, s6, 0x8000
	ds_read_b128 v[142:145], v106
	ds_read_b128 v[158:161], v108 offset:16384
	s_nop 0
	global_load_lds_dwordx4 v98, s[2:3]
	s_add_u32 m0, s6, 0x9000
	ds_read_b128 v[182:185], v108 offset:18432
	ds_read_b128 v[186:189], v108 offset:20480
	s_nop 0
	global_load_lds_dwordx4 v99, s[2:3]
	s_add_u32 m0, s6, 0xa000
	ds_read_b128 v[206:209], v108 offset:22528
	ds_read_b128 v[146:149], v106 offset:2048
	s_nop 0
	global_load_lds_dwordx4 v100, s[2:3]
	s_add_u32 m0, s6, 0xb000
	ds_read_b128 v[150:153], v106 offset:4096
	ds_read_b128 v[154:157], v106 offset:6144
	s_nop 0
	global_load_lds_dwordx4 v101, s[2:3]
	s_add_u32 m0, s6, 0xc000
	s_nop 0
	global_load_lds_dwordx4 v102, s[4:5]
	s_add_u32 m0, s6, 0xd000
	s_nop 0
	global_load_lds_dwordx4 v103, s[4:5]
	s_add_u32 m0, s6, 0xe000
	s_nop 0
	global_load_lds_dwordx4 v104, s[4:5]
	s_add_u32 m0, s6, 0xf000
	s_nop 0
	global_load_lds_dwordx4 v105, s[4:5]
	s_add_u32 s2, s2, 0x80
	s_addc_u32 s3, s3, 0
	s_add_u32 s4, s4, 0x80
	s_addc_u32 s5, s5, 0
	s_waitcnt lgkmcnt(0)
	v_mfma_f32_16x16x32_bf16 v[90:93], v[158:161], v[142:145], 0
	ds_read_b128 v[58:61], v107
	ds_read_b128 v[74:77], v109 offset:16384
	v_mfma_f32_16x16x32_bf16 v[54:57], v[182:185], v[142:145], 0
	v_mfma_f32_16x16x32_bf16 v[86:89], v[186:189], v[142:145], 0
	ds_read_b128 v[78:81], v109 offset:18432
	ds_read_b128 v[82:85], v109 offset:20480
	v_mfma_f32_16x16x32_bf16 v[50:53], v[206:209], v[142:145], 0
	v_mfma_f32_16x16x32_bf16 v[46:49], v[158:161], v[146:149], 0
	ds_read_b128 v[94:97], v109 offset:22528
	ds_read_b128 v[62:65], v107 offset:2048
	v_mfma_f32_16x16x32_bf16 v[38:41], v[182:185], v[146:149], 0
	v_mfma_f32_16x16x32_bf16 v[42:45], v[186:189], v[146:149], 0
	ds_read_b128 v[66:69], v107 offset:4096
	ds_read_b128 v[70:73], v107 offset:6144
	v_mfma_f32_16x16x32_bf16 v[34:37], v[206:209], v[146:149], 0
	v_mfma_f32_16x16x32_bf16 v[30:33], v[158:161], v[150:153], 0
	v_mfma_f32_16x16x32_bf16 v[22:25], v[182:185], v[150:153], 0
	v_mfma_f32_16x16x32_bf16 v[26:29], v[186:189], v[150:153], 0
	v_mfma_f32_16x16x32_bf16 v[18:21], v[206:209], v[150:153], 0
	v_mfma_f32_16x16x32_bf16 v[10:13], v[158:161], v[154:157], 0
	v_mfma_f32_16x16x32_bf16 v[2:5], v[182:185], v[154:157], 0
	v_mfma_f32_16x16x32_bf16 v[14:17], v[186:189], v[154:157], 0
	v_mfma_f32_16x16x32_bf16 v[6:9], v[206:209], v[154:157], 0
	s_waitcnt vmcnt(0) lgkmcnt(0)
	s_barrier
	s_movk_i32 s7, 7
.Lg9_loop:
	v_mfma_f32_16x16x32_bf16 v[90:93], v[74:77], v[58:61], v[90:93]
	s_mov_b32 m0, s6
	ds_read_b128 v[142:145], v106 offset:32768
	ds_read_b128 v[158:161], v108 offset:49152
	v_mfma_f32_16x16x32_bf16 v[54:57], v[78:81], v[58:61], v[54:57]
	global_load_lds_dwordx4 v98, s[2:3]
	v_mfma_f32_16x16x32_bf16 v[86:89], v[82:85], v[58:61], v[86:89]
	s_add_u32 m0, s6, 0x1000
	ds_read_b128 v[182:185], v108 offset:51200
	ds_read_b128 v[186:189], v108 offset:53248
	v_mfma_f32_16x16x32_bf16 v[50:53], v[94:97], v[58:61], v[50:53]
	global_load_lds_dwordx4 v99, s[2:3]
	v_mfma_f32_16x16x32_bf16 v[46:49], v[74:77], v[62:65], v[46:49]
	s_add_u32 m0, s6, 0x2000
	ds_read_b128 v[206:209], v108 offset:55296
	ds_read_b128 v[146:149], v106 offset:34816
	v_mfma_f32_16x16x32_bf16 v[38:41], v[78:81], v[62:65], v[38:41]
	global_load_lds_dwordx4 v100, s[2:3]
	v_mfma_f32_16x16x32_bf16 v[42:45], v[82:85], v[62:65], v[42:45]
	s_add_u32 m0, s6, 0x3000
	ds_read_b128 v[150:153], v106 offset:36864
	ds_read_b128 v[154:157], v106 offset:38912
	v_mfma_f32_16x16x32_bf16 v[34:37], v[94:97], v[62:65], v[34:37]
	global_load_lds_dwordx4 v101, s[2:3]
	v_mfma_f32_16x16x32_bf16 v[30:33], v[74:77], v[66:69], v[30:33]
	s_add_u32 m0, s6, 0x4000
	v_mfma_f32_16x16x32_bf16 v[22:25], v[78:81], v[66:69], v[22:25]
	global_load_lds_dwordx4 v102, s[4:5]
	v_mfma_f32_16x16x32_bf16 v[26:29], v[82:85], v[66:69], v[26:29]
	s_add_u32 m0, s6, 0x5000
	v_mfma_f32_16x16x32_bf16 v[18:21], v[94:97], v[66:69], v[18:21]
	global_load_lds_dwordx4 v103, s[4:5]
	v_mfma_f32_16x16x32_bf16 v[10:13], v[74:77], v[70:73], v[10:13]
	s_add_u32 m0, s6, 0x6000
	v_mfma_f32_16x16x32_bf16 v[2:5], v[78:81], v[70:73], v[2:5]
	global_load_lds_dwordx4 v104, s[4:5]
	v_mfma_f32_16x16x32_bf16 v[14:17], v[82:85], v[70:73], v[14:17]
	s_add_u32 m0, s6, 0x7000
	v_mfma_f32_16x16x32_bf16 v[6:9], v[94:97], v[70:73], v[6:9]
	global_load_lds_dwordx4 v105, s[4:5]
	s_add_u32 s2, s2, 0x80
	s_addc_u32 s3, s3, 0
	s_add_u32 s4, s4, 0x80
	s_addc_u32 s5, s5, 0
	s_waitcnt lgkmcnt(0)
	v_mfma_f32_16x16x32_bf16 v[90:93], v[158:161], v[142:145], v[90:93]
	ds_read_b128 v[58:61], v107 offset:32768
	ds_read_b128 v[74:77], v109 offset:49152
	v_mfma_f32_16x16x32_bf16 v[54:57], v[182:185], v[142:145], v[54:57]
	v_mfma_f32_16x16x32_bf16 v[86:89], v[186:189], v[142:145], v[86:89]
	ds_read_b128 v[78:81], v109 offset:51200
	ds_read_b128 v[82:85], v109 offset:53248
	v_mfma_f32_16x16x32_bf16 v[50:53], v[206:209], v[142:145], v[50:53]
	v_mfma_f32_16x16x32_bf16 v[46:49], v[158:161], v[146:149], v[46:49]
	ds_read_b128 v[94:97], v109 offset:55296
	ds_read_b128 v[62:65], v107 offset:34816
	v_mfma_f32_16x16x32_bf16 v[38:41], v[182:185], v[146:149], v[38:41]
	v_mfma_f32_16x16x32_bf16 v[42:45], v[186:189], v[146:149], v[42:45]
	ds_read_b128 v[66:69], v107 offset:36864
	ds_read_b128 v[70:73], v107 offset:38912
	v_mfma_f32_16x16x32_bf16 v[34:37], v[206:209], v[146:149], v[34:37]
	v_mfma_f32_16x16x32_bf16 v[30:33], v[158:161], v[150:153], v[30:33]
	v_mfma_f32_16x16x32_bf16 v[22:25], v[182:185], v[150:153], v[22:25]
	v_mfma_f32_16x16x32_bf16 v[26:29], v[186:189], v[150:153], v[26:29]
	v_mfma_f32_16x16x32_bf16 v[18:21], v[206:209], v[150:153], v[18:21]
	v_mfma_f32_16x16x32_bf16 v[10:13], v[158:161], v[154:157], v[10:13]
	v_mfma_f32_16x16x32_bf16 v[2:5], v[182:185], v[154:157], v[2:5]
	v_mfma_f32_16x16x32_bf16 v[14:17], v[186:189], v[154:157], v[14:17]
	v_mfma_f32_16x16x32_bf16 v[6:9], v[206:209], v[154:157], v[6:9]
	s_waitcnt vmcnt(0) lgkmcnt(0)
	s_barrier
	v_mfma_f32_16x16x32_bf16 v[90:93], v[74:77], v[58:61], v[90:93]
	s_add_u32 m0, s6, 0x8000
	ds_read_b128 v[142:145], v106
	ds_read_b128 v[158:161], v108 offset:16384
	v_mfma_f32_16x16x32_bf16 v[54:57], v[78:81], v[58:61], v[54:57]
	global_load_lds_dwordx4 v98, s[2:3]
	v_mfma_f32_16x16x32_bf16 v[86:89], v[82:85], v[58:61], v[86:89]
	s_add_u32 m0, s6, 0x9000
	ds_read_b128 v[182:185], v108 offset:18432
	ds_read_b128 v[186:189], v108 offset:20480
	v_mfma_f32_16x16x32_bf16 v[50:53], v[94:97], v[58:61], v[50:53]
	global_load_lds_dwordx4 v99, s[2:3]
	v_mfma_f32_16x16x32_bf16 v[46:49], v[74:77], v[62:65], v[46:49]
	s_add_u32 m0, s6, 0xa000
	ds_read_b128 v[206:209], v108 offset:22528
	ds_read_b128 v[146:149], v106 offset:2048
	v_mfma_f32_16x16x32_bf16 v[38:41], v[78:81], v[62:65], v[38:41]
	global_load_lds_dwordx4 v100, s[2:3]
	v_mfma_f32_16x16x32_bf16 v[42:45], v[82:85], v[62:65], v[42:45]
	s_add_u32 m0, s6, 0xb000
	ds_read_b128 v[150:153], v106 offset:4096
	ds_read_b128 v[154:157], v106 offset:6144
	v_mfma_f32_16x16x32_bf16 v[34:37], v[94:97], v[62:65], v[34:37]
	global_load_lds_dwordx4 v101, s[2:3]
	v_mfma_f32_16x16x32_bf16 v[30:33], v[74:77], v[66:69], v[30:33]
	s_add_u32 m0, s6, 0xc000
	v_mfma_f32_16x16x32_bf16 v[22:25], v[78:81], v[66:69], v[22:25]
	global_load_lds_dwordx4 v102, s[4:5]
	v_mfma_f32_16x16x32_bf16 v[26:29], v[82:85], v[66:69], v[26:29]
	s_add_u32 m0, s6, 0xd000
	v_mfma_f32_16x16x32_bf16 v[18:21], v[94:97], v[66:69], v[18:21]
	global_load_lds_dwordx4 v103, s[4:5]
	v_mfma_f32_16x16x32_bf16 v[10:13], v[74:77], v[70:73], v[10:13]
	s_add_u32 m0, s6, 0xe000
	v_mfma_f32_16x16x32_bf16 v[2:5], v[78:81], v[70:73], v[2:5]
	global_load_lds_dwordx4 v104, s[4:5]
	v_mfma_f32_16x16x32_bf16 v[14:17], v[82:85], v[70:73], v[14:17]
	s_add_u32 m0, s6, 0xf000
	v_mfma_f32_16x16x32_bf16 v[6:9], v[94:97], v[70:73], v[6:9]
	global_load_lds_dwordx4 v105, s[4:5]
	s_add_u32 s2, s2, 0x80
	s_addc_u32 s3, s3, 0
	s_add_u32 s4, s4, 0x80
	s_addc_u32 s5, s5, 0
	s_waitcnt lgkmcnt(0)
	v_mfma_f32_16x16x32_bf16 v[90:93], v[158:161], v[142:145], v[90:93]
	ds_read_b128 v[58:61], v107
	ds_read_b128 v[74:77], v109 offset:16384
	v_mfma_f32_16x16x32_bf16 v[54:57], v[182:185], v[142:145], v[54:57]
	v_mfma_f32_16x16x32_bf16 v[86:89], v[186:189], v[142:145], v[86:89]
	ds_read_b128 v[78:81], v109 offset:18432
	ds_read_b128 v[82:85], v109 offset:20480
	v_mfma_f32_16x16x32_bf16 v[50:53], v[206:209], v[142:145], v[50:53]
	v_mfma_f32_16x16x32_bf16 v[46:49], v[158:161], v[146:149], v[46:49]
	ds_read_b128 v[94:97], v109 offset:22528
	ds_read_b128 v[62:65], v107 offset:2048
	v_mfma_f32_16x16x32_bf16 v[38:41], v[182:185], v[146:149], v[38:41]
	v_mfma_f32_16x16x32_bf16 v[42:45], v[186:189], v[146:149], v[42:45]
	ds_read_b128 v[66:69], v107 offset:4096
	ds_read_b128 v[70:73], v107 offset:6144
	v_mfma_f32_16x16x32_bf16 v[34:37], v[206:209], v[146:149], v[34:37]
	v_mfma_f32_16x16x32_bf16 v[30:33], v[158:161], v[150:153], v[30:33]
	v_mfma_f32_16x16x32_bf16 v[22:25], v[182:185], v[150:153], v[22:25]
	v_mfma_f32_16x16x32_bf16 v[26:29], v[186:189], v[150:153], v[26:29]
	v_mfma_f32_16x16x32_bf16 v[18:21], v[206:209], v[150:153], v[18:21]
	v_mfma_f32_16x16x32_bf16 v[10:13], v[158:161], v[154:157], v[10:13]
	v_mfma_f32_16x16x32_bf16 v[2:5], v[182:185], v[154:157], v[2:5]
	v_mfma_f32_16x16x32_bf16 v[14:17], v[186:189], v[154:157], v[14:17]
	v_mfma_f32_16x16x32_bf16 v[6:9], v[206:209], v[154:157], v[6:9]
	s_add_i32 s7, s7, -1
	s_waitcnt vmcnt(0) lgkmcnt(0)
	s_barrier
	s_cmp_lg_u32 s7, 0
	s_cbranch_scc1 .Lg9_loop
	v_mfma_f32_16x16x32_bf16 v[90:93], v[74:77], v[58:61], v[90:93]
	ds_read_b128 v[142:145], v106 offset:32768
	ds_read_b128 v[158:161], v108 offset:49152
	v_mfma_f32_16x16x32_bf16 v[54:57], v[78:81], v[58:61], v[54:57]
	v_mfma_f32_16x16x32_bf16 v[86:89], v[82:85], v[58:61], v[86:89]
	ds_read_b128 v[182:185], v108 offset:51200
	ds_read_b128 v[186:189], v108 offset:53248
	v_mfma_f32_16x16x32_bf16 v[50:53], v[94:97], v[58:61], v[50:53]
	v_mfma_f32_16x16x32_bf16 v[46:49], v[74:77], v[62:65], v[46:49]
	ds_read_b128 v[206:209], v108 offset:55296
	ds_read_b128 v[146:149], v106 offset:34816
	v_mfma_f32_16x16x32_bf16 v[38:41], v[78:81], v[62:65], v[38:41]
	v_mfma_f32_16x16x32_bf16 v[42:45], v[82:85], v[62:65], v[42:45]
	ds_read_b128 v[150:153], v106 offset:36864
	ds_read_b128 v[154:157], v106 offset:38912
	v_mfma_f32_16x16x32_bf16 v[34:37], v[94:97], v[62:65], v[34:37]
	v_mfma_f32_16x16x32_bf16 v[30:33], v[74:77], v[66:69], v[30:33]
	v_mfma_f32_16x16x32_bf16 v[22:25], v[78:81], v[66:69], v[22:25]
	v_mfma_f32_16x16x32_bf16 v[26:29], v[82:85], v[66:69], v[26:29]
	v_mfma_f32_16x16x32_bf16 v[18:21], v[94:97], v[66:69], v[18:21]
	v_mfma_f32_16x16x32_bf16 v[10:13], v[74:77], v[70:73], v[10:13]
	v_mfma_f32_16x16x32_bf16 v[2:5], v[78:81], v[70:73], v[2:5]
	v_mfma_f32_16x16x32_bf16 v[14:17], v[82:85], v[70:73], v[14:17]
	v_mfma_f32_16x16x32_bf16 v[6:9], v[94:97], v[70:73], v[6:9]
	s_waitcnt lgkmcnt(0)
	v_mfma_f32_16x16x32_bf16 v[90:93], v[158:161], v[142:145], v[90:93]
	ds_read_b128 v[58:61], v107 offset:32768
	ds_read_b128 v[74:77], v109 offset:49152
	v_mfma_f32_16x16x32_bf16 v[54:57], v[182:185], v[142:145], v[54:57]
	v_mfma_f32_16x16x32_bf16 v[86:89], v[186:189], v[142:145], v[86:89]
	ds_read_b128 v[78:81], v109 offset:51200
	ds_read_b128 v[82:85], v109 offset:53248
	v_mfma_f32_16x16x32_bf16 v[50:53], v[206:209], v[142:145], v[50:53]
	v_mfma_f32_16x16x32_bf16 v[46:49], v[158:161], v[146:149], v[46:49]
	ds_read_b128 v[94:97], v109 offset:55296
	ds_read_b128 v[62:65], v107 offset:34816
	v_mfma_f32_16x16x32_bf16 v[38:41], v[182:185], v[146:149], v[38:41]
	v_mfma_f32_16x16x32_bf16 v[42:45], v[186:189], v[146:149], v[42:45]
	ds_read_b128 v[66:69], v107 offset:36864
	ds_read_b128 v[70:73], v107 offset:38912
	v_mfma_f32_16x16x32_bf16 v[34:37], v[206:209], v[146:149], v[34:37]
	v_mfma_f32_16x16x32_bf16 v[30:33], v[158:161], v[150:153], v[30:33]
	v_mfma_f32_16x16x32_bf16 v[22:25], v[182:185], v[150:153], v[22:25]
	v_mfma_f32_16x16x32_bf16 v[26:29], v[186:189], v[150:153], v[26:29]
	v_mfma_f32_16x16x32_bf16 v[18:21], v[206:209], v[150:153], v[18:21]
	v_mfma_f32_16x16x32_bf16 v[10:13], v[158:161], v[154:157], v[10:13]
	v_mfma_f32_16x16x32_bf16 v[2:5], v[182:185], v[154:157], v[2:5]
	v_mfma_f32_16x16x32_bf16 v[14:17], v[186:189], v[154:157], v[14:17]
	v_mfma_f32_16x16x32_bf16 v[6:9], v[206:209], v[154:157], v[6:9]
	s_waitcnt lgkmcnt(0)
	s_barrier
	v_mfma_f32_16x16x32_bf16 v[90:93], v[74:77], v[58:61], v[90:93]
	v_mfma_f32_16x16x32_bf16 v[54:57], v[78:81], v[58:61], v[54:57]
	v_mfma_f32_16x16x32_bf16 v[86:89], v[82:85], v[58:61], v[86:89]
	v_mfma_f32_16x16x32_bf16 v[50:53], v[94:97], v[58:61], v[50:53]
	v_mfma_f32_16x16x32_bf16 v[46:49], v[74:77], v[62:65], v[46:49]
	v_mfma_f32_16x16x32_bf16 v[38:41], v[78:81], v[62:65], v[38:41]
	v_mfma_f32_16x16x32_bf16 v[42:45], v[82:85], v[62:65], v[42:45]
	v_mfma_f32_16x16x32_bf16 v[34:37], v[94:97], v[62:65], v[34:37]
	v_mfma_f32_16x16x32_bf16 v[30:33], v[74:77], v[66:69], v[30:33]
	v_mfma_f32_16x16x32_bf16 v[22:25], v[78:81], v[66:69], v[22:25]
	v_mfma_f32_16x16x32_bf16 v[26:29], v[82:85], v[66:69], v[26:29]
	v_mfma_f32_16x16x32_bf16 v[18:21], v[94:97], v[66:69], v[18:21]
	v_mfma_f32_16x16x32_bf16 v[10:13], v[74:77], v[70:73], v[10:13]
	v_mfma_f32_16x16x32_bf16 v[2:5], v[78:81], v[70:73], v[2:5]
	v_mfma_f32_16x16x32_bf16 v[14:17], v[82:85], v[70:73], v[14:17]
	v_mfma_f32_16x16x32_bf16 v[6:9], v[94:97], v[70:73], v[6:9]
	s_nop 7
	s_nop 2
	s_mov_b32 s21, 0x33000
	s_branch .LBB0_58

.LBB0_82:
	v_lshrrev_b32_e32 v2, 6, v134
	v_lshlrev_b32_e32 v3, 4, v134
	v_bfe_u32 v0, v134, 3, 3
	v_and_b32_e32 v3, 0x70, v3
	v_and_b32_e32 v4, 8, v2
	v_or3_b32 v135, v3, v4, v0
	v_ashrrev_i32_e32 v0, 7, v134
	v_bfi_b32 v136, -8, v0, v2
	v_mul_u32_u24_e32 v0, 0x22000, v135
	v_mov_b64_e32 v[2:3], s[54:55]
	s_mov_b32 s2, 0x44000
	v_lshlrev_b32_e32 v0, 1, v0
	v_mad_i64_i32 v[6:7], s[2:3], v136, s2, v[2:3]
	v_mov_b32_e32 v2, v163
	v_lshl_add_u64 v[4:5], s[80:81], 0, v[0:1]
	s_mov_b32 s4, 0x22000
	v_ashrrev_i32_e32 v3, 3, v2
	v_lshlrev_b32_e32 v0, 4, v2
	v_mad_i64_i32 v[4:5], s[2:3], v3, s43, v[4:5]
	v_and_b32_e32 v0, 0x70, v0
	v_lshl_add_u64 v[130:131], v[4:5], 0, v[0:1]
	v_mad_i64_i32 v[4:5], s[2:3], v3, s43, v[6:7]
	v_lshl_add_u64 v[132:133], v[4:5], 0, v[0:1]
	v_and_b32_e32 v110, 7, v163
	v_bfe_u32 v111, v163, 4, 3
	v_xor_b32_e32 v111, v111, v110
	v_sub_u32_e32 v111, v111, v110
	v_lshlrev_b32_e32 v111, 4, v111
	v_lshrrev_b32_e32 v112, 6, v163
	v_lshlrev_b32_e32 v112, 10, v112
	v_readfirstlane_b32 s2, v130
	v_readfirstlane_b32 s3, v131
	v_readfirstlane_b32 s4, v132
	v_readfirstlane_b32 s5, v133
	v_readfirstlane_b32 s6, v112
	s_nop 3
	v_subrev_u32_e32 v98, s2, v130
	v_subrev_u32_e32 v102, s4, v132
	v_add_u32_e32 v98, v98, v111
	v_add_u32_e32 v102, v102, v111
	v_add_u32_e32 v99, 0x11000, v98
	v_add_u32_e32 v103, 0x11000, v102
	v_add_u32_e32 v100, 0x22000, v98
	v_add_u32_e32 v104, 0x22000, v102
	v_add_u32_e32 v101, 0x33000, v98
	v_add_u32_e32 v105, 0x33000, v102
	v_lshlrev_b32_e32 v110, 3, v163
	v_lshlrev_b32_e32 v111, 7, v163
	v_and_b32_e32 v112, 0x2000, v111
	v_and_b32_e32 v111, 0x780, v111
	v_and_b32_e32 v107, 64, v110
	v_xor_b32_e32 v110, v110, v163
	v_and_b32_e32 v110, 48, v110
	v_or3_b32 v110, v111, v107, v110
	v_lshlrev_b32_e32 v111, 6, v163
	v_and_b32_e32 v111, 0xffffe000, v111
	v_or_b32_e32 v108, v110, v112
	v_or_b32_e32 v106, v110, v111
	v_xor_b32_e32 v107, 64, v106
	v_xor_b32_e32 v109, 64, v108
	s_mov_b32 m0, s6
	s_nop 0
	global_load_lds_dwordx4 v98, s[2:3]
	s_add_u32 m0, s6, 0x1000
	s_nop 0
	global_load_lds_dwordx4 v99, s[2:3]
	s_add_u32 m0, s6, 0x2000
	s_nop 0
	global_load_lds_dwordx4 v100, s[2:3]
	s_add_u32 m0, s6, 0x3000
	s_nop 0
	global_load_lds_dwordx4 v101, s[2:3]
	s_add_u32 m0, s6, 0x4000
	s_nop 0
	global_load_lds_dwordx4 v102, s[4:5]
	s_add_u32 m0, s6, 0x5000
	s_nop 0
	global_load_lds_dwordx4 v103, s[4:5]
	s_add_u32 m0, s6, 0x6000
	s_nop 0
	global_load_lds_dwordx4 v104, s[4:5]
	s_add_u32 m0, s6, 0x7000
	s_nop 0
	global_load_lds_dwordx4 v105, s[4:5]
	s_add_u32 s2, s2, 0x80
	s_addc_u32 s3, s3, 0
	s_add_u32 s4, s4, 0x80
	s_addc_u32 s5, s5, 0
	s_waitcnt vmcnt(0)
	s_barrier
	s_add_u32 m0, s6, 0x8000
	ds_read_b128 v[142:145], v106
	ds_read_b128 v[158:161], v108 offset:16384
	s_nop 0
	global_load_lds_dwordx4 v98, s[2:3]
	s_add_u32 m0, s6, 0x9000
	ds_read_b128 v[182:185], v108 offset:18432
	ds_read_b128 v[186:189], v108 offset:20480
	s_nop 0
	global_load_lds_dwordx4 v99, s[2:3]
	s_add_u32 m0, s6, 0xa000
	ds_read_b128 v[206:209], v108 offset:22528
	ds_read_b128 v[146:149], v106 offset:2048
	s_nop 0
	global_load_lds_dwordx4 v100, s[2:3]
	s_add_u32 m0, s6, 0xb000
	ds_read_b128 v[150:153], v106 offset:4096
	ds_read_b128 v[154:157], v106 offset:6144
	s_nop 0
	global_load_lds_dwordx4 v101, s[2:3]
	s_add_u32 m0, s6, 0xc000
	s_nop 0
	global_load_lds_dwordx4 v102, s[4:5]
	s_add_u32 m0, s6, 0xd000
	s_nop 0
	global_load_lds_dwordx4 v103, s[4:5]
	s_add_u32 m0, s6, 0xe000
	s_nop 0
	global_load_lds_dwordx4 v104, s[4:5]
	s_add_u32 m0, s6, 0xf000
	s_nop 0
	global_load_lds_dwordx4 v105, s[4:5]
	s_add_u32 s2, s2, 0x80
	s_addc_u32 s3, s3, 0
	s_add_u32 s4, s4, 0x80
	s_addc_u32 s5, s5, 0
	s_waitcnt lgkmcnt(0)
	v_mfma_f32_16x16x32_bf16 v[94:97], v[158:161], v[142:145], 0
	ds_read_b128 v[34:37], v107
	ds_read_b128 v[54:57], v109 offset:16384
	v_mfma_f32_16x16x32_bf16 v[90:93], v[182:185], v[142:145], 0
	v_mfma_f32_16x16x32_bf16 v[86:89], v[186:189], v[142:145], 0
	ds_read_b128 v[62:65], v109 offset:18432
	ds_read_b128 v[66:69], v109 offset:20480
	v_mfma_f32_16x16x32_bf16 v[82:85], v[206:209], v[142:145], 0
	v_mfma_f32_16x16x32_bf16 v[74:77], v[158:161], v[146:149], 0
	ds_read_b128 v[78:81], v109 offset:22528
	ds_read_b128 v[38:41], v107 offset:2048
	v_mfma_f32_16x16x32_bf16 v[70:73], v[182:185], v[146:149], 0
	v_mfma_f32_16x16x32_bf16 v[58:61], v[186:189], v[146:149], 0
	ds_read_b128 v[46:49], v107 offset:4096
	ds_read_b128 v[50:53], v107 offset:6144
	v_mfma_f32_16x16x32_bf16 v[42:45], v[206:209], v[146:149], 0
	v_mfma_f32_16x16x32_bf16 v[30:33], v[158:161], v[150:153], 0
	v_mfma_f32_16x16x32_bf16 v[26:29], v[182:185], v[150:153], 0
	v_mfma_f32_16x16x32_bf16 v[22:25], v[186:189], v[150:153], 0
	v_mfma_f32_16x16x32_bf16 v[18:21], v[206:209], v[150:153], 0
	v_mfma_f32_16x16x32_bf16 v[14:17], v[158:161], v[154:157], 0
	v_mfma_f32_16x16x32_bf16 v[10:13], v[182:185], v[154:157], 0
	v_mfma_f32_16x16x32_bf16 v[6:9], v[186:189], v[154:157], 0
	v_mfma_f32_16x16x32_bf16 v[2:5], v[206:209], v[154:157], 0
	s_waitcnt vmcnt(0) lgkmcnt(0)
	s_barrier
	s_movk_i32 s7, 7
.Lg7_loop:
	v_mfma_f32_16x16x32_bf16 v[94:97], v[54:57], v[34:37], v[94:97]
	s_mov_b32 m0, s6
	ds_read_b128 v[142:145], v106 offset:32768
	ds_read_b128 v[158:161], v108 offset:49152
	v_mfma_f32_16x16x32_bf16 v[90:93], v[62:65], v[34:37], v[90:93]
	global_load_lds_dwordx4 v98, s[2:3]
	v_mfma_f32_16x16x32_bf16 v[86:89], v[66:69], v[34:37], v[86:89]
	s_add_u32 m0, s6, 0x1000
	ds_read_b128 v[182:185], v108 offset:51200
	ds_read_b128 v[186:189], v108 offset:53248
	v_mfma_f32_16x16x32_bf16 v[82:85], v[78:81], v[34:37], v[82:85]
	global_load_lds_dwordx4 v99, s[2:3]
	v_mfma_f32_16x16x32_bf16 v[74:77], v[54:57], v[38:41], v[74:77]
	s_add_u32 m0, s6, 0x2000
	ds_read_b128 v[206:209], v108 offset:55296
	ds_read_b128 v[146:149], v106 offset:34816
	v_mfma_f32_16x16x32_bf16 v[70:73], v[62:65], v[38:41], v[70:73]
	global_load_lds_dwordx4 v100, s[2:3]
	v_mfma_f32_16x16x32_bf16 v[58:61], v[66:69], v[38:41], v[58:61]
	s_add_u32 m0, s6, 0x3000
	ds_read_b128 v[150:153], v106 offset:36864
	ds_read_b128 v[154:157], v106 offset:38912
	v_mfma_f32_16x16x32_bf16 v[42:45], v[78:81], v[38:41], v[42:45]
	global_load_lds_dwordx4 v101, s[2:3]
	v_mfma_f32_16x16x32_bf16 v[30:33], v[54:57], v[46:49], v[30:33]
	s_add_u32 m0, s6, 0x4000
	v_mfma_f32_16x16x32_bf16 v[26:29], v[62:65], v[46:49], v[26:29]
	global_load_lds_dwordx4 v102, s[4:5]
	v_mfma_f32_16x16x32_bf16 v[22:25], v[66:69], v[46:49], v[22:25]
	s_add_u32 m0, s6, 0x5000
	v_mfma_f32_16x16x32_bf16 v[18:21], v[78:81], v[46:49], v[18:21]
	global_load_lds_dwordx4 v103, s[4:5]
	v_mfma_f32_16x16x32_bf16 v[14:17], v[54:57], v[50:53], v[14:17]
	s_add_u32 m0, s6, 0x6000
	v_mfma_f32_16x16x32_bf16 v[10:13], v[62:65], v[50:53], v[10:13]
	global_load_lds_dwordx4 v104, s[4:5]
	v_mfma_f32_16x16x32_bf16 v[6:9], v[66:69], v[50:53], v[6:9]
	s_add_u32 m0, s6, 0x7000
	v_mfma_f32_16x16x32_bf16 v[2:5], v[78:81], v[50:53], v[2:5]
	global_load_lds_dwordx4 v105, s[4:5]
	s_add_u32 s2, s2, 0x80
	s_addc_u32 s3, s3, 0
	s_add_u32 s4, s4, 0x80
	s_addc_u32 s5, s5, 0
	s_waitcnt lgkmcnt(0)
	v_mfma_f32_16x16x32_bf16 v[94:97], v[158:161], v[142:145], v[94:97]
	ds_read_b128 v[34:37], v107 offset:32768
	ds_read_b128 v[54:57], v109 offset:49152
	v_mfma_f32_16x16x32_bf16 v[90:93], v[182:185], v[142:145], v[90:93]
	v_mfma_f32_16x16x32_bf16 v[86:89], v[186:189], v[142:145], v[86:89]
	ds_read_b128 v[62:65], v109 offset:51200
	ds_read_b128 v[66:69], v109 offset:53248
	v_mfma_f32_16x16x32_bf16 v[82:85], v[206:209], v[142:145], v[82:85]
	v_mfma_f32_16x16x32_bf16 v[74:77], v[158:161], v[146:149], v[74:77]
	ds_read_b128 v[78:81], v109 offset:55296
	ds_read_b128 v[38:41], v107 offset:34816
	v_mfma_f32_16x16x32_bf16 v[70:73], v[182:185], v[146:149], v[70:73]
	v_mfma_f32_16x16x32_bf16 v[58:61], v[186:189], v[146:149], v[58:61]
	ds_read_b128 v[46:49], v107 offset:36864
	ds_read_b128 v[50:53], v107 offset:38912
	v_mfma_f32_16x16x32_bf16 v[42:45], v[206:209], v[146:149], v[42:45]
	v_mfma_f32_16x16x32_bf16 v[30:33], v[158:161], v[150:153], v[30:33]
	v_mfma_f32_16x16x32_bf16 v[26:29], v[182:185], v[150:153], v[26:29]
	v_mfma_f32_16x16x32_bf16 v[22:25], v[186:189], v[150:153], v[22:25]
	v_mfma_f32_16x16x32_bf16 v[18:21], v[206:209], v[150:153], v[18:21]
	v_mfma_f32_16x16x32_bf16 v[14:17], v[158:161], v[154:157], v[14:17]
	v_mfma_f32_16x16x32_bf16 v[10:13], v[182:185], v[154:157], v[10:13]
	v_mfma_f32_16x16x32_bf16 v[6:9], v[186:189], v[154:157], v[6:9]
	v_mfma_f32_16x16x32_bf16 v[2:5], v[206:209], v[154:157], v[2:5]
	s_waitcnt vmcnt(0) lgkmcnt(0)
	s_barrier
	v_mfma_f32_16x16x32_bf16 v[94:97], v[54:57], v[34:37], v[94:97]
	s_add_u32 m0, s6, 0x8000
	ds_read_b128 v[142:145], v106
	ds_read_b128 v[158:161], v108 offset:16384
	v_mfma_f32_16x16x32_bf16 v[90:93], v[62:65], v[34:37], v[90:93]
	global_load_lds_dwordx4 v98, s[2:3]
	v_mfma_f32_16x16x32_bf16 v[86:89], v[66:69], v[34:37], v[86:89]
	s_add_u32 m0, s6, 0x9000
	ds_read_b128 v[182:185], v108 offset:18432
	ds_read_b128 v[186:189], v108 offset:20480
	v_mfma_f32_16x16x32_bf16 v[82:85], v[78:81], v[34:37], v[82:85]
	global_load_lds_dwordx4 v99, s[2:3]
	v_mfma_f32_16x16x32_bf16 v[74:77], v[54:57], v[38:41], v[74:77]
	s_add_u32 m0, s6, 0xa000
	ds_read_b128 v[206:209], v108 offset:22528
	ds_read_b128 v[146:149], v106 offset:2048
	v_mfma_f32_16x16x32_bf16 v[70:73], v[62:65], v[38:41], v[70:73]
	global_load_lds_dwordx4 v100, s[2:3]
	v_mfma_f32_16x16x32_bf16 v[58:61], v[66:69], v[38:41], v[58:61]
	s_add_u32 m0, s6, 0xb000
	ds_read_b128 v[150:153], v106 offset:4096
	ds_read_b128 v[154:157], v106 offset:6144
	v_mfma_f32_16x16x32_bf16 v[42:45], v[78:81], v[38:41], v[42:45]
	global_load_lds_dwordx4 v101, s[2:3]
	v_mfma_f32_16x16x32_bf16 v[30:33], v[54:57], v[46:49], v[30:33]
	s_add_u32 m0, s6, 0xc000
	v_mfma_f32_16x16x32_bf16 v[26:29], v[62:65], v[46:49], v[26:29]
	global_load_lds_dwordx4 v102, s[4:5]
	v_mfma_f32_16x16x32_bf16 v[22:25], v[66:69], v[46:49], v[22:25]
	s_add_u32 m0, s6, 0xd000
	v_mfma_f32_16x16x32_bf16 v[18:21], v[78:81], v[46:49], v[18:21]
	global_load_lds_dwordx4 v103, s[4:5]
	v_mfma_f32_16x16x32_bf16 v[14:17], v[54:57], v[50:53], v[14:17]
	s_add_u32 m0, s6, 0xe000
	v_mfma_f32_16x16x32_bf16 v[10:13], v[62:65], v[50:53], v[10:13]
	global_load_lds_dwordx4 v104, s[4:5]
	v_mfma_f32_16x16x32_bf16 v[6:9], v[66:69], v[50:53], v[6:9]
	s_add_u32 m0, s6, 0xf000
	v_mfma_f32_16x16x32_bf16 v[2:5], v[78:81], v[50:53], v[2:5]
	global_load_lds_dwordx4 v105, s[4:5]
	s_add_u32 s2, s2, 0x80
	s_addc_u32 s3, s3, 0
	s_add_u32 s4, s4, 0x80
	s_addc_u32 s5, s5, 0
	s_waitcnt lgkmcnt(0)
	v_mfma_f32_16x16x32_bf16 v[94:97], v[158:161], v[142:145], v[94:97]
	ds_read_b128 v[34:37], v107
	ds_read_b128 v[54:57], v109 offset:16384
	v_mfma_f32_16x16x32_bf16 v[90:93], v[182:185], v[142:145], v[90:93]
	v_mfma_f32_16x16x32_bf16 v[86:89], v[186:189], v[142:145], v[86:89]
	ds_read_b128 v[62:65], v109 offset:18432
	ds_read_b128 v[66:69], v109 offset:20480
	v_mfma_f32_16x16x32_bf16 v[82:85], v[206:209], v[142:145], v[82:85]
	v_mfma_f32_16x16x32_bf16 v[74:77], v[158:161], v[146:149], v[74:77]
	ds_read_b128 v[78:81], v109 offset:22528
	ds_read_b128 v[38:41], v107 offset:2048
	v_mfma_f32_16x16x32_bf16 v[70:73], v[182:185], v[146:149], v[70:73]
	v_mfma_f32_16x16x32_bf16 v[58:61], v[186:189], v[146:149], v[58:61]
	ds_read_b128 v[46:49], v107 offset:4096
	ds_read_b128 v[50:53], v107 offset:6144
	v_mfma_f32_16x16x32_bf16 v[42:45], v[206:209], v[146:149], v[42:45]
	v_mfma_f32_16x16x32_bf16 v[30:33], v[158:161], v[150:153], v[30:33]
	v_mfma_f32_16x16x32_bf16 v[26:29], v[182:185], v[150:153], v[26:29]
	v_mfma_f32_16x16x32_bf16 v[22:25], v[186:189], v[150:153], v[22:25]
	v_mfma_f32_16x16x32_bf16 v[18:21], v[206:209], v[150:153], v[18:21]
	v_mfma_f32_16x16x32_bf16 v[14:17], v[158:161], v[154:157], v[14:17]
	v_mfma_f32_16x16x32_bf16 v[10:13], v[182:185], v[154:157], v[10:13]
	v_mfma_f32_16x16x32_bf16 v[6:9], v[186:189], v[154:157], v[6:9]
	v_mfma_f32_16x16x32_bf16 v[2:5], v[206:209], v[154:157], v[2:5]
	s_add_i32 s7, s7, -1
	s_waitcnt vmcnt(0) lgkmcnt(0)
	s_barrier
	s_cmp_lg_u32 s7, 0
	s_cbranch_scc1 .Lg7_loop
	v_mfma_f32_16x16x32_bf16 v[94:97], v[54:57], v[34:37], v[94:97]
	ds_read_b128 v[142:145], v106 offset:32768
	ds_read_b128 v[158:161], v108 offset:49152
	v_mfma_f32_16x16x32_bf16 v[90:93], v[62:65], v[34:37], v[90:93]
	v_mfma_f32_16x16x32_bf16 v[86:89], v[66:69], v[34:37], v[86:89]
	ds_read_b128 v[182:185], v108 offset:51200
	ds_read_b128 v[186:189], v108 offset:53248
	v_mfma_f32_16x16x32_bf16 v[82:85], v[78:81], v[34:37], v[82:85]
	v_mfma_f32_16x16x32_bf16 v[74:77], v[54:57], v[38:41], v[74:77]
	ds_read_b128 v[206:209], v108 offset:55296
	ds_read_b128 v[146:149], v106 offset:34816
	v_mfma_f32_16x16x32_bf16 v[70:73], v[62:65], v[38:41], v[70:73]
	v_mfma_f32_16x16x32_bf16 v[58:61], v[66:69], v[38:41], v[58:61]
	ds_read_b128 v[150:153], v106 offset:36864
	ds_read_b128 v[154:157], v106 offset:38912
	v_mfma_f32_16x16x32_bf16 v[42:45], v[78:81], v[38:41], v[42:45]
	v_mfma_f32_16x16x32_bf16 v[30:33], v[54:57], v[46:49], v[30:33]
	v_mfma_f32_16x16x32_bf16 v[26:29], v[62:65], v[46:49], v[26:29]
	v_mfma_f32_16x16x32_bf16 v[22:25], v[66:69], v[46:49], v[22:25]
	v_mfma_f32_16x16x32_bf16 v[18:21], v[78:81], v[46:49], v[18:21]
	v_mfma_f32_16x16x32_bf16 v[14:17], v[54:57], v[50:53], v[14:17]
	v_mfma_f32_16x16x32_bf16 v[10:13], v[62:65], v[50:53], v[10:13]
	v_mfma_f32_16x16x32_bf16 v[6:9], v[66:69], v[50:53], v[6:9]
	v_mfma_f32_16x16x32_bf16 v[2:5], v[78:81], v[50:53], v[2:5]
	s_waitcnt lgkmcnt(0)
	v_mfma_f32_16x16x32_bf16 v[94:97], v[158:161], v[142:145], v[94:97]
	ds_read_b128 v[34:37], v107 offset:32768
	ds_read_b128 v[54:57], v109 offset:49152
	v_mfma_f32_16x16x32_bf16 v[90:93], v[182:185], v[142:145], v[90:93]
	v_mfma_f32_16x16x32_bf16 v[86:89], v[186:189], v[142:145], v[86:89]
	ds_read_b128 v[62:65], v109 offset:51200
	ds_read_b128 v[66:69], v109 offset:53248
	v_mfma_f32_16x16x32_bf16 v[82:85], v[206:209], v[142:145], v[82:85]
	v_mfma_f32_16x16x32_bf16 v[74:77], v[158:161], v[146:149], v[74:77]
	ds_read_b128 v[78:81], v109 offset:55296
	ds_read_b128 v[38:41], v107 offset:34816
	v_mfma_f32_16x16x32_bf16 v[70:73], v[182:185], v[146:149], v[70:73]
	v_mfma_f32_16x16x32_bf16 v[58:61], v[186:189], v[146:149], v[58:61]
	ds_read_b128 v[46:49], v107 offset:36864
	ds_read_b128 v[50:53], v107 offset:38912
	v_mfma_f32_16x16x32_bf16 v[42:45], v[206:209], v[146:149], v[42:45]
	v_mfma_f32_16x16x32_bf16 v[30:33], v[158:161], v[150:153], v[30:33]
	v_mfma_f32_16x16x32_bf16 v[26:29], v[182:185], v[150:153], v[26:29]
	v_mfma_f32_16x16x32_bf16 v[22:25], v[186:189], v[150:153], v[22:25]
	v_mfma_f32_16x16x32_bf16 v[18:21], v[206:209], v[150:153], v[18:21]
	v_mfma_f32_16x16x32_bf16 v[14:17], v[158:161], v[154:157], v[14:17]
	v_mfma_f32_16x16x32_bf16 v[10:13], v[182:185], v[154:157], v[10:13]
	v_mfma_f32_16x16x32_bf16 v[6:9], v[186:189], v[154:157], v[6:9]
	v_mfma_f32_16x16x32_bf16 v[2:5], v[206:209], v[154:157], v[2:5]
	s_waitcnt lgkmcnt(0)
	s_barrier
	v_mfma_f32_16x16x32_bf16 v[94:97], v[54:57], v[34:37], v[94:97]
	v_mfma_f32_16x16x32_bf16 v[90:93], v[62:65], v[34:37], v[90:93]
	v_mfma_f32_16x16x32_bf16 v[86:89], v[66:69], v[34:37], v[86:89]
	v_mfma_f32_16x16x32_bf16 v[82:85], v[78:81], v[34:37], v[82:85]
	v_mfma_f32_16x16x32_bf16 v[74:77], v[54:57], v[38:41], v[74:77]
	v_mfma_f32_16x16x32_bf16 v[70:73], v[62:65], v[38:41], v[70:73]
	v_mfma_f32_16x16x32_bf16 v[58:61], v[66:69], v[38:41], v[58:61]
	v_mfma_f32_16x16x32_bf16 v[42:45], v[78:81], v[38:41], v[42:45]
	v_mfma_f32_16x16x32_bf16 v[30:33], v[54:57], v[46:49], v[30:33]
	v_mfma_f32_16x16x32_bf16 v[26:29], v[62:65], v[46:49], v[26:29]
	v_mfma_f32_16x16x32_bf16 v[22:25], v[66:69], v[46:49], v[22:25]
	v_mfma_f32_16x16x32_bf16 v[18:21], v[78:81], v[46:49], v[18:21]
	v_mfma_f32_16x16x32_bf16 v[14:17], v[54:57], v[50:53], v[14:17]
	v_mfma_f32_16x16x32_bf16 v[10:13], v[62:65], v[50:53], v[10:13]
	v_mfma_f32_16x16x32_bf16 v[6:9], v[66:69], v[50:53], v[6:9]
	v_mfma_f32_16x16x32_bf16 v[2:5], v[78:81], v[50:53], v[2:5]
	s_nop 7
	s_nop 2
	s_mov_b32 s21, 0x33000
	s_branch .LBB0_81

.LBB0_273:
	v_mov_b32_e32 v0, v163
	s_bfe_u32 s7, s3, 0x30002
	v_mov_b64_e32 v[4:5], s[78:79]
	v_ashrrev_i32_e32 v2, 4, v0
	v_lshl_add_u32 v2, s7, 6, v2
	v_ashrrev_i32_e32 v3, 31, v2
	v_lshlrev_b64 v[2:3], 5, v[2:3]
	v_or_b32_e32 v2, s0, v2
	s_ashr_i32 s4, s3, 6
	s_bfe_u32 s5, s3, 0x10005
	v_mad_u64_u32 v[4:5], s[8:9], v2, s93, v[4:5]
	s_cmp_lt_u32 s3, 64
	s_movk_i32 s8, 0x1400
	s_mul_i32 s9, s4, 0x108000
	s_cselect_b32 s40, s8, 0x1500
	s_mul_hi_i32 s8, s4, 0x108000
	s_add_u32 s9, s76, s9
	s_addc_u32 s8, s77, s8
	s_mul_i32 s10, s5, 0x84000
	v_mad_i32_i24 v5, v3, s93, v5
	s_add_u32 s9, s9, s10
	v_lshl_add_u64 v[2:3], v[4:5], 0, s[40:41]
	v_lshlrev_b32_e32 v4, 4, v0
	s_addc_u32 s10, s8, 0
	v_and_b32_e32 v0, 0x80, v4
	s_add_u32 s8, s9, s2
	v_lshl_add_u64 v[2:3], v[2:3], 0, v[0:1]
	v_and_b32_e32 v0, 0x70, v4
	s_addc_u32 s9, s10, 0
	v_mov_b32_e32 v30, v163
	v_lshl_add_u64 v[130:131], v[2:3], 0, v[0:1]
	v_mov_b64_e32 v[2:3], s[8:9]
	v_ashrrev_i32_e32 v31, 3, v30
	s_movk_i32 s8, 0x1080
	v_lshlrev_b32_e32 v0, 4, v30
	v_mad_i64_i32 v[2:3], s[8:9], v31, s8, v[2:3]
	v_and_b32_e32 v0, 0x70, v0
	s_mov_b32 s15, 0x660000
	v_lshl_add_u64 v[132:133], v[2:3], 0, v[0:1]
	v_and_b32_e32 v110, 7, v163
	v_bfe_u32 v111, v163, 4, 3
	v_xor_b32_e32 v111, v111, v110
	v_sub_u32_e32 v111, v111, v110
	v_lshlrev_b32_e32 v111, 4, v111
	v_lshrrev_b32_e32 v112, 6, v163
	v_lshlrev_b32_e32 v112, 10, v112
	v_readfirstlane_b32 s8, v130
	v_readfirstlane_b32 s9, v131
	v_readfirstlane_b32 s10, v132
	v_readfirstlane_b32 s11, v133
	v_readfirstlane_b32 s12, v112
	s_nop 3
	v_subrev_u32_e32 v98, s8, v130
	v_subrev_u32_e32 v102, s10, v132
	v_add_u32_e32 v98, v98, v111
	v_add_u32_e32 v102, v102, v111
	v_add_u32_e32 v99, 0x660000, v98
	v_add_u32_e32 v103, 0x21000, v102
	v_add_u32_e32 v100, 0xcc0000, v98
	v_add_u32_e32 v104, 0x42000, v102
	v_add_u32_e32 v101, 0x1320000, v98
	v_add_u32_e32 v105, 0x63000, v102
	v_lshlrev_b32_e32 v110, 3, v163
	v_lshlrev_b32_e32 v111, 7, v163
	v_and_b32_e32 v112, 0x2000, v111
	v_and_b32_e32 v111, 0x780, v111
	v_and_b32_e32 v107, 64, v110
	v_xor_b32_e32 v110, v110, v163
	v_and_b32_e32 v110, 48, v110
	v_or3_b32 v110, v111, v107, v110
	v_lshlrev_b32_e32 v111, 6, v163
	v_and_b32_e32 v111, 0xffffe000, v111
	v_or_b32_e32 v108, v110, v112
	v_or_b32_e32 v106, v110, v111
	v_xor_b32_e32 v107, 64, v106
	v_xor_b32_e32 v109, 64, v108
	s_mov_b32 m0, s12
	s_nop 0
	global_load_lds_dwordx4 v98, s[8:9]
	s_add_u32 m0, s12, 0x1000
	s_nop 0
	global_load_lds_dwordx4 v99, s[8:9]
	s_add_u32 m0, s12, 0x2000
	s_nop 0
	global_load_lds_dwordx4 v100, s[8:9]
	s_add_u32 m0, s12, 0x3000
	s_nop 0
	global_load_lds_dwordx4 v101, s[8:9]
	s_add_u32 m0, s12, 0x4000
	s_nop 0
	global_load_lds_dwordx4 v102, s[10:11]
	s_add_u32 m0, s12, 0x5000
	s_nop 0
	global_load_lds_dwordx4 v103, s[10:11]
	s_add_u32 m0, s12, 0x6000
	s_nop 0
	global_load_lds_dwordx4 v104, s[10:11]
	s_add_u32 m0, s12, 0x7000
	s_nop 0
	global_load_lds_dwordx4 v105, s[10:11]
	s_add_u32 s8, s8, 0x3300
	s_addc_u32 s9, s9, 0
	s_add_u32 s10, s10, 0x80
	s_addc_u32 s11, s11, 0
	s_waitcnt vmcnt(0)
	s_barrier
	s_add_u32 m0, s12, 0x8000
	ds_read_b128 v[138:141], v106
	ds_read_b128 v[154:157], v108 offset:16384
	s_nop 0
	global_load_lds_dwordx4 v98, s[8:9]
	s_add_u32 m0, s12, 0x9000
	ds_read_b128 v[158:161], v108 offset:18432
	ds_read_b128 v[182:185], v108 offset:20480
	s_nop 0
	global_load_lds_dwordx4 v99, s[8:9]
	s_add_u32 m0, s12, 0xa000
	ds_read_b128 v[186:189], v108 offset:22528
	ds_read_b128 v[142:145], v106 offset:2048
	s_nop 0
	global_load_lds_dwordx4 v100, s[8:9]
	s_add_u32 m0, s12, 0xb000
	ds_read_b128 v[146:149], v106 offset:4096
	ds_read_b128 v[150:153], v106 offset:6144
	s_nop 0
	global_load_lds_dwordx4 v101, s[8:9]
	s_add_u32 m0, s12, 0xc000
	s_nop 0
	global_load_lds_dwordx4 v102, s[10:11]
	s_add_u32 m0, s12, 0xd000
	s_nop 0
	global_load_lds_dwordx4 v103, s[10:11]
	s_add_u32 m0, s12, 0xe000
	s_nop 0
	global_load_lds_dwordx4 v104, s[10:11]
	s_add_u32 m0, s12, 0xf000
	s_nop 0
	global_load_lds_dwordx4 v105, s[10:11]
	s_add_u32 s8, s8, 0x3300
	s_addc_u32 s9, s9, 0
	s_add_u32 s10, s10, 0x80
	s_addc_u32 s11, s11, 0
	s_waitcnt lgkmcnt(0)
	v_mfma_f32_16x16x32_bf16 v[94:97], v[154:157], v[138:141], 0
	ds_read_b128 v[2:5], v107
	ds_read_b128 v[18:21], v109 offset:16384
	v_mfma_f32_16x16x32_bf16 v[90:93], v[158:161], v[138:141], 0
	v_mfma_f32_16x16x32_bf16 v[86:89], v[182:185], v[138:141], 0
	ds_read_b128 v[22:25], v109 offset:18432
	ds_read_b128 v[26:29], v109 offset:20480
	v_mfma_f32_16x16x32_bf16 v[82:85], v[186:189], v[138:141], 0
	v_mfma_f32_16x16x32_bf16 v[78:81], v[154:157], v[142:145], 0
	ds_read_b128 v[54:57], v109 offset:22528
	ds_read_b128 v[6:9], v107 offset:2048
	v_mfma_f32_16x16x32_bf16 v[70:73], v[158:161], v[142:145], 0
	v_mfma_f32_16x16x32_bf16 v[66:69], v[182:185], v[142:145], 0
	ds_read_b128 v[10:13], v107 offset:4096
	ds_read_b128 v[14:17], v107 offset:6144
	v_mfma_f32_16x16x32_bf16 v[62:65], v[186:189], v[142:145], 0
	v_mfma_f32_16x16x32_bf16 v[58:61], v[154:157], v[146:149], 0
	v_mfma_f32_16x16x32_bf16 v[50:53], v[158:161], v[146:149], 0
	v_mfma_f32_16x16x32_bf16 v[46:49], v[182:185], v[146:149], 0
	v_mfma_f32_16x16x32_bf16 v[42:45], v[186:189], v[146:149], 0
	v_mfma_f32_16x16x32_bf16 v[38:41], v[154:157], v[150:153], 0
	v_mfma_f32_16x16x32_bf16 v[34:37], v[158:161], v[150:153], 0
	v_mfma_f32_16x16x32_bf16 v[30:33], v[182:185], v[150:153], 0
	v_mfma_f32_16x16x32_bf16 v[74:77], v[186:189], v[150:153], 0
	s_waitcnt vmcnt(0) lgkmcnt(0)
	s_barrier
	s_movk_i32 s13, 3
.Lgc_loop:
	v_mfma_f32_16x16x32_bf16 v[94:97], v[18:21], v[2:5], v[94:97]
	s_mov_b32 m0, s12
	ds_read_b128 v[138:141], v106 offset:32768
	ds_read_b128 v[154:157], v108 offset:49152
	v_mfma_f32_16x16x32_bf16 v[90:93], v[22:25], v[2:5], v[90:93]
	global_load_lds_dwordx4 v98, s[8:9]
	v_mfma_f32_16x16x32_bf16 v[86:89], v[26:29], v[2:5], v[86:89]
	s_add_u32 m0, s12, 0x1000
	ds_read_b128 v[158:161], v108 offset:51200
	ds_read_b128 v[182:185], v108 offset:53248
	v_mfma_f32_16x16x32_bf16 v[82:85], v[54:57], v[2:5], v[82:85]
	global_load_lds_dwordx4 v99, s[8:9]
	v_mfma_f32_16x16x32_bf16 v[78:81], v[18:21], v[6:9], v[78:81]
	s_add_u32 m0, s12, 0x2000
	ds_read_b128 v[186:189], v108 offset:55296
	ds_read_b128 v[142:145], v106 offset:34816
	v_mfma_f32_16x16x32_bf16 v[70:73], v[22:25], v[6:9], v[70:73]
	global_load_lds_dwordx4 v100, s[8:9]
	v_mfma_f32_16x16x32_bf16 v[66:69], v[26:29], v[6:9], v[66:69]
	s_add_u32 m0, s12, 0x3000
	ds_read_b128 v[146:149], v106 offset:36864
	ds_read_b128 v[150:153], v106 offset:38912
	v_mfma_f32_16x16x32_bf16 v[62:65], v[54:57], v[6:9], v[62:65]
	global_load_lds_dwordx4 v101, s[8:9]
	v_mfma_f32_16x16x32_bf16 v[58:61], v[18:21], v[10:13], v[58:61]
	s_add_u32 m0, s12, 0x4000
	v_mfma_f32_16x16x32_bf16 v[50:53], v[22:25], v[10:13], v[50:53]
	global_load_lds_dwordx4 v102, s[10:11]
	v_mfma_f32_16x16x32_bf16 v[46:49], v[26:29], v[10:13], v[46:49]
	s_add_u32 m0, s12, 0x5000
	v_mfma_f32_16x16x32_bf16 v[42:45], v[54:57], v[10:13], v[42:45]
	global_load_lds_dwordx4 v103, s[10:11]
	v_mfma_f32_16x16x32_bf16 v[38:41], v[18:21], v[14:17], v[38:41]
	s_add_u32 m0, s12, 0x6000
	v_mfma_f32_16x16x32_bf16 v[34:37], v[22:25], v[14:17], v[34:37]
	global_load_lds_dwordx4 v104, s[10:11]
	v_mfma_f32_16x16x32_bf16 v[30:33], v[26:29], v[14:17], v[30:33]
	s_add_u32 m0, s12, 0x7000
	v_mfma_f32_16x16x32_bf16 v[74:77], v[54:57], v[14:17], v[74:77]
	global_load_lds_dwordx4 v105, s[10:11]
	s_add_u32 s8, s8, 0x3300
	s_addc_u32 s9, s9, 0
	s_add_u32 s10, s10, 0x80
	s_addc_u32 s11, s11, 0
	s_waitcnt lgkmcnt(0)
	v_mfma_f32_16x16x32_bf16 v[94:97], v[154:157], v[138:141], v[94:97]
	ds_read_b128 v[2:5], v107 offset:32768
	ds_read_b128 v[18:21], v109 offset:49152
	v_mfma_f32_16x16x32_bf16 v[90:93], v[158:161], v[138:141], v[90:93]
	v_mfma_f32_16x16x32_bf16 v[86:89], v[182:185], v[138:141], v[86:89]
	ds_read_b128 v[22:25], v109 offset:51200
	ds_read_b128 v[26:29], v109 offset:53248
	v_mfma_f32_16x16x32_bf16 v[82:85], v[186:189], v[138:141], v[82:85]
	v_mfma_f32_16x16x32_bf16 v[78:81], v[154:157], v[142:145], v[78:81]
	ds_read_b128 v[54:57], v109 offset:55296
	ds_read_b128 v[6:9], v107 offset:34816
	v_mfma_f32_16x16x32_bf16 v[70:73], v[158:161], v[142:145], v[70:73]
	v_mfma_f32_16x16x32_bf16 v[66:69], v[182:185], v[142:145], v[66:69]
	ds_read_b128 v[10:13], v107 offset:36864
	ds_read_b128 v[14:17], v107 offset:38912
	v_mfma_f32_16x16x32_bf16 v[62:65], v[186:189], v[142:145], v[62:65]
	v_mfma_f32_16x16x32_bf16 v[58:61], v[154:157], v[146:149], v[58:61]
	v_mfma_f32_16x16x32_bf16 v[50:53], v[158:161], v[146:149], v[50:53]
	v_mfma_f32_16x16x32_bf16 v[46:49], v[182:185], v[146:149], v[46:49]
	v_mfma_f32_16x16x32_bf16 v[42:45], v[186:189], v[146:149], v[42:45]
	v_mfma_f32_16x16x32_bf16 v[38:41], v[154:157], v[150:153], v[38:41]
	v_mfma_f32_16x16x32_bf16 v[34:37], v[158:161], v[150:153], v[34:37]
	v_mfma_f32_16x16x32_bf16 v[30:33], v[182:185], v[150:153], v[30:33]
	v_mfma_f32_16x16x32_bf16 v[74:77], v[186:189], v[150:153], v[74:77]
	s_waitcnt vmcnt(0) lgkmcnt(0)
	s_barrier
	v_mfma_f32_16x16x32_bf16 v[94:97], v[18:21], v[2:5], v[94:97]
	s_add_u32 m0, s12, 0x8000
	ds_read_b128 v[138:141], v106
	ds_read_b128 v[154:157], v108 offset:16384
	v_mfma_f32_16x16x32_bf16 v[90:93], v[22:25], v[2:5], v[90:93]
	global_load_lds_dwordx4 v98, s[8:9]
	v_mfma_f32_16x16x32_bf16 v[86:89], v[26:29], v[2:5], v[86:89]
	s_add_u32 m0, s12, 0x9000
	ds_read_b128 v[158:161], v108 offset:18432
	ds_read_b128 v[182:185], v108 offset:20480
	v_mfma_f32_16x16x32_bf16 v[82:85], v[54:57], v[2:5], v[82:85]
	global_load_lds_dwordx4 v99, s[8:9]
	v_mfma_f32_16x16x32_bf16 v[78:81], v[18:21], v[6:9], v[78:81]
	s_add_u32 m0, s12, 0xa000
	ds_read_b128 v[186:189], v108 offset:22528
	ds_read_b128 v[142:145], v106 offset:2048
	v_mfma_f32_16x16x32_bf16 v[70:73], v[22:25], v[6:9], v[70:73]
	global_load_lds_dwordx4 v100, s[8:9]
	v_mfma_f32_16x16x32_bf16 v[66:69], v[26:29], v[6:9], v[66:69]
	s_add_u32 m0, s12, 0xb000
	ds_read_b128 v[146:149], v106 offset:4096
	ds_read_b128 v[150:153], v106 offset:6144
	v_mfma_f32_16x16x32_bf16 v[62:65], v[54:57], v[6:9], v[62:65]
	global_load_lds_dwordx4 v101, s[8:9]
	v_mfma_f32_16x16x32_bf16 v[58:61], v[18:21], v[10:13], v[58:61]
	s_add_u32 m0, s12, 0xc000
	v_mfma_f32_16x16x32_bf16 v[50:53], v[22:25], v[10:13], v[50:53]
	global_load_lds_dwordx4 v102, s[10:11]
	v_mfma_f32_16x16x32_bf16 v[46:49], v[26:29], v[10:13], v[46:49]
	s_add_u32 m0, s12, 0xd000
	v_mfma_f32_16x16x32_bf16 v[42:45], v[54:57], v[10:13], v[42:45]
	global_load_lds_dwordx4 v103, s[10:11]
	v_mfma_f32_16x16x32_bf16 v[38:41], v[18:21], v[14:17], v[38:41]
	s_add_u32 m0, s12, 0xe000
	v_mfma_f32_16x16x32_bf16 v[34:37], v[22:25], v[14:17], v[34:37]
	global_load_lds_dwordx4 v104, s[10:11]
	v_mfma_f32_16x16x32_bf16 v[30:33], v[26:29], v[14:17], v[30:33]
	s_add_u32 m0, s12, 0xf000
	v_mfma_f32_16x16x32_bf16 v[74:77], v[54:57], v[14:17], v[74:77]
	global_load_lds_dwordx4 v105, s[10:11]
	s_add_u32 s8, s8, 0x3300
	s_addc_u32 s9, s9, 0
	s_add_u32 s10, s10, 0x80
	s_addc_u32 s11, s11, 0
	s_waitcnt lgkmcnt(0)
	v_mfma_f32_16x16x32_bf16 v[94:97], v[154:157], v[138:141], v[94:97]
	ds_read_b128 v[2:5], v107
	ds_read_b128 v[18:21], v109 offset:16384
	v_mfma_f32_16x16x32_bf16 v[90:93], v[158:161], v[138:141], v[90:93]
	v_mfma_f32_16x16x32_bf16 v[86:89], v[182:185], v[138:141], v[86:89]
	ds_read_b128 v[22:25], v109 offset:18432
	ds_read_b128 v[26:29], v109 offset:20480
	v_mfma_f32_16x16x32_bf16 v[82:85], v[186:189], v[138:141], v[82:85]
	v_mfma_f32_16x16x32_bf16 v[78:81], v[154:157], v[142:145], v[78:81]
	ds_read_b128 v[54:57], v109 offset:22528
	ds_read_b128 v[6:9], v107 offset:2048
	v_mfma_f32_16x16x32_bf16 v[70:73], v[158:161], v[142:145], v[70:73]
	v_mfma_f32_16x16x32_bf16 v[66:69], v[182:185], v[142:145], v[66:69]
	ds_read_b128 v[10:13], v107 offset:4096
	ds_read_b128 v[14:17], v107 offset:6144
	v_mfma_f32_16x16x32_bf16 v[62:65], v[186:189], v[142:145], v[62:65]
	v_mfma_f32_16x16x32_bf16 v[58:61], v[154:157], v[146:149], v[58:61]
	v_mfma_f32_16x16x32_bf16 v[50:53], v[158:161], v[146:149], v[50:53]
	v_mfma_f32_16x16x32_bf16 v[46:49], v[182:185], v[146:149], v[46:49]
	v_mfma_f32_16x16x32_bf16 v[42:45], v[186:189], v[146:149], v[42:45]
	v_mfma_f32_16x16x32_bf16 v[38:41], v[154:157], v[150:153], v[38:41]
	v_mfma_f32_16x16x32_bf16 v[34:37], v[158:161], v[150:153], v[34:37]
	v_mfma_f32_16x16x32_bf16 v[30:33], v[182:185], v[150:153], v[30:33]
	v_mfma_f32_16x16x32_bf16 v[74:77], v[186:189], v[150:153], v[74:77]
	s_add_i32 s13, s13, -1
	s_waitcnt vmcnt(0) lgkmcnt(0)
	s_barrier
	s_cmp_lg_u32 s13, 0
	s_cbranch_scc1 .Lgc_loop
	v_mfma_f32_16x16x32_bf16 v[94:97], v[18:21], v[2:5], v[94:97]
	ds_read_b128 v[138:141], v106 offset:32768
	ds_read_b128 v[154:157], v108 offset:49152
	v_mfma_f32_16x16x32_bf16 v[90:93], v[22:25], v[2:5], v[90:93]
	v_mfma_f32_16x16x32_bf16 v[86:89], v[26:29], v[2:5], v[86:89]
	ds_read_b128 v[158:161], v108 offset:51200
	ds_read_b128 v[182:185], v108 offset:53248
	v_mfma_f32_16x16x32_bf16 v[82:85], v[54:57], v[2:5], v[82:85]
	v_mfma_f32_16x16x32_bf16 v[78:81], v[18:21], v[6:9], v[78:81]
	ds_read_b128 v[186:189], v108 offset:55296
	ds_read_b128 v[142:145], v106 offset:34816
	v_mfma_f32_16x16x32_bf16 v[70:73], v[22:25], v[6:9], v[70:73]
	v_mfma_f32_16x16x32_bf16 v[66:69], v[26:29], v[6:9], v[66:69]
	ds_read_b128 v[146:149], v106 offset:36864
	ds_read_b128 v[150:153], v106 offset:38912
	v_mfma_f32_16x16x32_bf16 v[62:65], v[54:57], v[6:9], v[62:65]
	v_mfma_f32_16x16x32_bf16 v[58:61], v[18:21], v[10:13], v[58:61]
	v_mfma_f32_16x16x32_bf16 v[50:53], v[22:25], v[10:13], v[50:53]
	v_mfma_f32_16x16x32_bf16 v[46:49], v[26:29], v[10:13], v[46:49]
	v_mfma_f32_16x16x32_bf16 v[42:45], v[54:57], v[10:13], v[42:45]
	v_mfma_f32_16x16x32_bf16 v[38:41], v[18:21], v[14:17], v[38:41]
	v_mfma_f32_16x16x32_bf16 v[34:37], v[22:25], v[14:17], v[34:37]
	v_mfma_f32_16x16x32_bf16 v[30:33], v[26:29], v[14:17], v[30:33]
	v_mfma_f32_16x16x32_bf16 v[74:77], v[54:57], v[14:17], v[74:77]
	s_waitcnt lgkmcnt(0)
	v_mfma_f32_16x16x32_bf16 v[94:97], v[154:157], v[138:141], v[94:97]
	ds_read_b128 v[2:5], v107 offset:32768
	ds_read_b128 v[18:21], v109 offset:49152
	v_mfma_f32_16x16x32_bf16 v[90:93], v[158:161], v[138:141], v[90:93]
	v_mfma_f32_16x16x32_bf16 v[86:89], v[182:185], v[138:141], v[86:89]
	ds_read_b128 v[22:25], v109 offset:51200
	ds_read_b128 v[26:29], v109 offset:53248
	v_mfma_f32_16x16x32_bf16 v[82:85], v[186:189], v[138:141], v[82:85]
	v_mfma_f32_16x16x32_bf16 v[78:81], v[154:157], v[142:145], v[78:81]
	ds_read_b128 v[54:57], v109 offset:55296
	ds_read_b128 v[6:9], v107 offset:34816
	v_mfma_f32_16x16x32_bf16 v[70:73], v[158:161], v[142:145], v[70:73]
	v_mfma_f32_16x16x32_bf16 v[66:69], v[182:185], v[142:145], v[66:69]
	ds_read_b128 v[10:13], v107 offset:36864
	ds_read_b128 v[14:17], v107 offset:38912
	v_mfma_f32_16x16x32_bf16 v[62:65], v[186:189], v[142:145], v[62:65]
	v_mfma_f32_16x16x32_bf16 v[58:61], v[154:157], v[146:149], v[58:61]
	v_mfma_f32_16x16x32_bf16 v[50:53], v[158:161], v[146:149], v[50:53]
	v_mfma_f32_16x16x32_bf16 v[46:49], v[182:185], v[146:149], v[46:49]
	v_mfma_f32_16x16x32_bf16 v[42:45], v[186:189], v[146:149], v[42:45]
	v_mfma_f32_16x16x32_bf16 v[38:41], v[154:157], v[150:153], v[38:41]
	v_mfma_f32_16x16x32_bf16 v[34:37], v[158:161], v[150:153], v[34:37]
	v_mfma_f32_16x16x32_bf16 v[30:33], v[182:185], v[150:153], v[30:33]
	v_mfma_f32_16x16x32_bf16 v[74:77], v[186:189], v[150:153], v[74:77]
	s_waitcnt lgkmcnt(0)
	s_barrier
	v_mfma_f32_16x16x32_bf16 v[94:97], v[18:21], v[2:5], v[94:97]
	v_mfma_f32_16x16x32_bf16 v[90:93], v[22:25], v[2:5], v[90:93]
	v_mfma_f32_16x16x32_bf16 v[86:89], v[26:29], v[2:5], v[86:89]
	v_mfma_f32_16x16x32_bf16 v[82:85], v[54:57], v[2:5], v[82:85]
	v_mfma_f32_16x16x32_bf16 v[78:81], v[18:21], v[6:9], v[78:81]
	v_mfma_f32_16x16x32_bf16 v[70:73], v[22:25], v[6:9], v[70:73]
	v_mfma_f32_16x16x32_bf16 v[66:69], v[26:29], v[6:9], v[66:69]
	v_mfma_f32_16x16x32_bf16 v[62:65], v[54:57], v[6:9], v[62:65]
	v_mfma_f32_16x16x32_bf16 v[58:61], v[18:21], v[10:13], v[58:61]
	v_mfma_f32_16x16x32_bf16 v[50:53], v[22:25], v[10:13], v[50:53]
	v_mfma_f32_16x16x32_bf16 v[46:49], v[26:29], v[10:13], v[46:49]
	v_mfma_f32_16x16x32_bf16 v[42:45], v[54:57], v[10:13], v[42:45]
	v_mfma_f32_16x16x32_bf16 v[38:41], v[18:21], v[14:17], v[38:41]
	v_mfma_f32_16x16x32_bf16 v[34:37], v[22:25], v[14:17], v[34:37]
	v_mfma_f32_16x16x32_bf16 v[30:33], v[26:29], v[14:17], v[30:33]
	v_mfma_f32_16x16x32_bf16 v[74:77], v[54:57], v[14:17], v[74:77]
	s_nop 7
	s_nop 2
	s_branch .LBB0_272

.LBB0_398:
	v_mov_b64_e32 v[2:3], s[80:81]
	s_mov_b32 s4, 0x44000
	v_mad_u64_u32 v[4:5], s[0:1], v136, s4, v[2:3]
	v_mov_b64_e32 v[2:3], s[46:47]
	v_mad_i64_i32 v[6:7], s[0:1], v135, s4, v[2:3]
	v_mov_b32_e32 v2, v163
	s_mov_b32 s4, 0x22000
	v_ashrrev_i32_e32 v3, 3, v2
	v_lshlrev_b32_e32 v0, 4, v2
	v_mad_i64_i32 v[4:5], s[0:1], v3, s43, v[4:5]
	v_and_b32_e32 v0, 0x70, v0
	v_lshl_add_u64 v[130:131], v[4:5], 0, v[0:1]
	v_mad_i64_i32 v[4:5], s[0:1], v3, s43, v[6:7]
	v_lshl_add_u64 v[132:133], v[4:5], 0, v[0:1]
	v_and_b32_e32 v110, 7, v163
	v_bfe_u32 v111, v163, 4, 3
	v_xor_b32_e32 v111, v111, v110
	v_sub_u32_e32 v111, v111, v110
	v_lshlrev_b32_e32 v111, 4, v111
	v_lshrrev_b32_e32 v112, 6, v163
	v_lshlrev_b32_e32 v112, 10, v112
	v_readfirstlane_b32 s0, v130
	v_readfirstlane_b32 s1, v131
	v_readfirstlane_b32 s4, v132
	v_readfirstlane_b32 s5, v133
	v_readfirstlane_b32 s8, v112
	s_nop 3
	v_subrev_u32_e32 v98, s0, v130
	v_subrev_u32_e32 v102, s4, v132
	v_add_u32_e32 v98, v98, v111
	v_add_u32_e32 v102, v102, v111
	v_add_u32_e32 v99, 0x11000, v98
	v_add_u32_e32 v103, 0x11000, v102
	v_add_u32_e32 v100, 0x22000, v98
	v_add_u32_e32 v104, 0x22000, v102
	v_add_u32_e32 v101, 0x33000, v98
	v_add_u32_e32 v105, 0x33000, v102
	v_lshlrev_b32_e32 v110, 3, v163
	v_lshlrev_b32_e32 v111, 7, v163
	v_and_b32_e32 v112, 0x2000, v111
	v_and_b32_e32 v111, 0x780, v111
	v_and_b32_e32 v107, 64, v110
	v_xor_b32_e32 v110, v110, v163
	v_and_b32_e32 v110, 48, v110
	v_or3_b32 v110, v111, v107, v110
	v_lshlrev_b32_e32 v111, 6, v163
	v_and_b32_e32 v111, 0xffffe000, v111
	v_or_b32_e32 v108, v110, v112
	v_or_b32_e32 v106, v110, v111
	v_xor_b32_e32 v107, 64, v106
	v_xor_b32_e32 v109, 64, v108
	s_mov_b32 m0, s8
	s_nop 0
	global_load_lds_dwordx4 v98, s[0:1]
	s_add_u32 m0, s8, 0x1000
	s_nop 0
	global_load_lds_dwordx4 v99, s[0:1]
	s_add_u32 m0, s8, 0x2000
	s_nop 0
	global_load_lds_dwordx4 v100, s[0:1]
	s_add_u32 m0, s8, 0x3000
	s_nop 0
	global_load_lds_dwordx4 v101, s[0:1]
	s_add_u32 m0, s8, 0x4000
	s_nop 0
	global_load_lds_dwordx4 v102, s[4:5]
	s_add_u32 m0, s8, 0x5000
	s_nop 0
	global_load_lds_dwordx4 v103, s[4:5]
	s_add_u32 m0, s8, 0x6000
	s_nop 0
	global_load_lds_dwordx4 v104, s[4:5]
	s_add_u32 m0, s8, 0x7000
	s_nop 0
	global_load_lds_dwordx4 v105, s[4:5]
	s_add_u32 s0, s0, 0x80
	s_addc_u32 s1, s1, 0
	s_add_u32 s4, s4, 0x80
	s_addc_u32 s5, s5, 0
	s_waitcnt vmcnt(0)
	s_barrier
	s_add_u32 m0, s8, 0x8000
	ds_read_b128 v[142:145], v106
	ds_read_b128 v[158:161], v108 offset:16384
	s_nop 0
	global_load_lds_dwordx4 v98, s[0:1]
	s_add_u32 m0, s8, 0x9000
	ds_read_b128 v[182:185], v108 offset:18432
	ds_read_b128 v[186:189], v108 offset:20480
	s_nop 0
	global_load_lds_dwordx4 v99, s[0:1]
	s_add_u32 m0, s8, 0xa000
	ds_read_b128 v[206:209], v108 offset:22528
	ds_read_b128 v[146:149], v106 offset:2048
	s_nop 0
	global_load_lds_dwordx4 v100, s[0:1]
	s_add_u32 m0, s8, 0xb000
	ds_read_b128 v[150:153], v106 offset:4096
	ds_read_b128 v[154:157], v106 offset:6144
	s_nop 0
	global_load_lds_dwordx4 v101, s[0:1]
	s_add_u32 m0, s8, 0xc000
	s_nop 0
	global_load_lds_dwordx4 v102, s[4:5]
	s_add_u32 m0, s8, 0xd000
	s_nop 0
	global_load_lds_dwordx4 v103, s[4:5]
	s_add_u32 m0, s8, 0xe000
	s_nop 0
	global_load_lds_dwordx4 v104, s[4:5]
	s_add_u32 m0, s8, 0xf000
	s_nop 0
	global_load_lds_dwordx4 v105, s[4:5]
	s_add_u32 s0, s0, 0x80
	s_addc_u32 s1, s1, 0
	s_add_u32 s4, s4, 0x80
	s_addc_u32 s5, s5, 0
	s_waitcnt lgkmcnt(0)
	v_mfma_f32_16x16x32_bf16 v[94:97], v[158:161], v[142:145], 0
	ds_read_b128 v[50:53], v107
	ds_read_b128 v[66:69], v109 offset:16384
	v_mfma_f32_16x16x32_bf16 v[90:93], v[182:185], v[142:145], 0
	v_mfma_f32_16x16x32_bf16 v[86:89], v[186:189], v[142:145], 0
	ds_read_b128 v[70:73], v109 offset:18432
	ds_read_b128 v[78:81], v109 offset:20480
	v_mfma_f32_16x16x32_bf16 v[74:77], v[206:209], v[142:145], 0
	v_mfma_f32_16x16x32_bf16 v[46:49], v[158:161], v[146:149], 0
	ds_read_b128 v[82:85], v109 offset:22528
	ds_read_b128 v[54:57], v107 offset:2048
	v_mfma_f32_16x16x32_bf16 v[42:45], v[182:185], v[146:149], 0
	v_mfma_f32_16x16x32_bf16 v[38:41], v[186:189], v[146:149], 0
	ds_read_b128 v[58:61], v107 offset:4096
	ds_read_b128 v[62:65], v107 offset:6144
	v_mfma_f32_16x16x32_bf16 v[34:37], v[206:209], v[146:149], 0
	v_mfma_f32_16x16x32_bf16 v[30:33], v[158:161], v[150:153], 0
	v_mfma_f32_16x16x32_bf16 v[26:29], v[182:185], v[150:153], 0
	v_mfma_f32_16x16x32_bf16 v[22:25], v[186:189], v[150:153], 0
	v_mfma_f32_16x16x32_bf16 v[18:21], v[206:209], v[150:153], 0
	v_mfma_f32_16x16x32_bf16 v[14:17], v[158:161], v[154:157], 0
	v_mfma_f32_16x16x32_bf16 v[10:13], v[182:185], v[154:157], 0
	v_mfma_f32_16x16x32_bf16 v[2:5], v[186:189], v[154:157], 0
	v_mfma_f32_16x16x32_bf16 v[6:9], v[206:209], v[154:157], 0
	s_waitcnt vmcnt(0) lgkmcnt(0)
	s_barrier
	s_movk_i32 s9, 7
.Lg1_loop:
	v_mfma_f32_16x16x32_bf16 v[94:97], v[66:69], v[50:53], v[94:97]
	s_mov_b32 m0, s8
	ds_read_b128 v[142:145], v106 offset:32768
	ds_read_b128 v[158:161], v108 offset:49152
	v_mfma_f32_16x16x32_bf16 v[90:93], v[70:73], v[50:53], v[90:93]
	global_load_lds_dwordx4 v98, s[0:1]
	v_mfma_f32_16x16x32_bf16 v[86:89], v[78:81], v[50:53], v[86:89]
	s_add_u32 m0, s8, 0x1000
	ds_read_b128 v[182:185], v108 offset:51200
	ds_read_b128 v[186:189], v108 offset:53248
	v_mfma_f32_16x16x32_bf16 v[74:77], v[82:85], v[50:53], v[74:77]
	global_load_lds_dwordx4 v99, s[0:1]
	v_mfma_f32_16x16x32_bf16 v[46:49], v[66:69], v[54:57], v[46:49]
	s_add_u32 m0, s8, 0x2000
	ds_read_b128 v[206:209], v108 offset:55296
	ds_read_b128 v[146:149], v106 offset:34816
	v_mfma_f32_16x16x32_bf16 v[42:45], v[70:73], v[54:57], v[42:45]
	global_load_lds_dwordx4 v100, s[0:1]
	v_mfma_f32_16x16x32_bf16 v[38:41], v[78:81], v[54:57], v[38:41]
	s_add_u32 m0, s8, 0x3000
	ds_read_b128 v[150:153], v106 offset:36864
	ds_read_b128 v[154:157], v106 offset:38912
	v_mfma_f32_16x16x32_bf16 v[34:37], v[82:85], v[54:57], v[34:37]
	global_load_lds_dwordx4 v101, s[0:1]
	v_mfma_f32_16x16x32_bf16 v[30:33], v[66:69], v[58:61], v[30:33]
	s_add_u32 m0, s8, 0x4000
	v_mfma_f32_16x16x32_bf16 v[26:29], v[70:73], v[58:61], v[26:29]
	global_load_lds_dwordx4 v102, s[4:5]
	v_mfma_f32_16x16x32_bf16 v[22:25], v[78:81], v[58:61], v[22:25]
	s_add_u32 m0, s8, 0x5000
	v_mfma_f32_16x16x32_bf16 v[18:21], v[82:85], v[58:61], v[18:21]
	global_load_lds_dwordx4 v103, s[4:5]
	v_mfma_f32_16x16x32_bf16 v[14:17], v[66:69], v[62:65], v[14:17]
	s_add_u32 m0, s8, 0x6000
	v_mfma_f32_16x16x32_bf16 v[10:13], v[70:73], v[62:65], v[10:13]
	global_load_lds_dwordx4 v104, s[4:5]
	v_mfma_f32_16x16x32_bf16 v[2:5], v[78:81], v[62:65], v[2:5]
	s_add_u32 m0, s8, 0x7000
	v_mfma_f32_16x16x32_bf16 v[6:9], v[82:85], v[62:65], v[6:9]
	global_load_lds_dwordx4 v105, s[4:5]
	s_add_u32 s0, s0, 0x80
	s_addc_u32 s1, s1, 0
	s_add_u32 s4, s4, 0x80
	s_addc_u32 s5, s5, 0
	s_waitcnt lgkmcnt(0)
	v_mfma_f32_16x16x32_bf16 v[94:97], v[158:161], v[142:145], v[94:97]
	ds_read_b128 v[50:53], v107 offset:32768
	ds_read_b128 v[66:69], v109 offset:49152
	v_mfma_f32_16x16x32_bf16 v[90:93], v[182:185], v[142:145], v[90:93]
	v_mfma_f32_16x16x32_bf16 v[86:89], v[186:189], v[142:145], v[86:89]
	ds_read_b128 v[70:73], v109 offset:51200
	ds_read_b128 v[78:81], v109 offset:53248
	v_mfma_f32_16x16x32_bf16 v[74:77], v[206:209], v[142:145], v[74:77]
	v_mfma_f32_16x16x32_bf16 v[46:49], v[158:161], v[146:149], v[46:49]
	ds_read_b128 v[82:85], v109 offset:55296
	ds_read_b128 v[54:57], v107 offset:34816
	v_mfma_f32_16x16x32_bf16 v[42:45], v[182:185], v[146:149], v[42:45]
	v_mfma_f32_16x16x32_bf16 v[38:41], v[186:189], v[146:149], v[38:41]
	ds_read_b128 v[58:61], v107 offset:36864
	ds_read_b128 v[62:65], v107 offset:38912
	v_mfma_f32_16x16x32_bf16 v[34:37], v[206:209], v[146:149], v[34:37]
	v_mfma_f32_16x16x32_bf16 v[30:33], v[158:161], v[150:153], v[30:33]
	v_mfma_f32_16x16x32_bf16 v[26:29], v[182:185], v[150:153], v[26:29]
	v_mfma_f32_16x16x32_bf16 v[22:25], v[186:189], v[150:153], v[22:25]
	v_mfma_f32_16x16x32_bf16 v[18:21], v[206:209], v[150:153], v[18:21]
	v_mfma_f32_16x16x32_bf16 v[14:17], v[158:161], v[154:157], v[14:17]
	v_mfma_f32_16x16x32_bf16 v[10:13], v[182:185], v[154:157], v[10:13]
	v_mfma_f32_16x16x32_bf16 v[2:5], v[186:189], v[154:157], v[2:5]
	v_mfma_f32_16x16x32_bf16 v[6:9], v[206:209], v[154:157], v[6:9]
	s_waitcnt vmcnt(0) lgkmcnt(0)
	s_barrier
	v_mfma_f32_16x16x32_bf16 v[94:97], v[66:69], v[50:53], v[94:97]
	s_add_u32 m0, s8, 0x8000
	ds_read_b128 v[142:145], v106
	ds_read_b128 v[158:161], v108 offset:16384
	v_mfma_f32_16x16x32_bf16 v[90:93], v[70:73], v[50:53], v[90:93]
	global_load_lds_dwordx4 v98, s[0:1]
	v_mfma_f32_16x16x32_bf16 v[86:89], v[78:81], v[50:53], v[86:89]
	s_add_u32 m0, s8, 0x9000
	ds_read_b128 v[182:185], v108 offset:18432
	ds_read_b128 v[186:189], v108 offset:20480
	v_mfma_f32_16x16x32_bf16 v[74:77], v[82:85], v[50:53], v[74:77]
	global_load_lds_dwordx4 v99, s[0:1]
	v_mfma_f32_16x16x32_bf16 v[46:49], v[66:69], v[54:57], v[46:49]
	s_add_u32 m0, s8, 0xa000
	ds_read_b128 v[206:209], v108 offset:22528
	ds_read_b128 v[146:149], v106 offset:2048
	v_mfma_f32_16x16x32_bf16 v[42:45], v[70:73], v[54:57], v[42:45]
	global_load_lds_dwordx4 v100, s[0:1]
	v_mfma_f32_16x16x32_bf16 v[38:41], v[78:81], v[54:57], v[38:41]
	s_add_u32 m0, s8, 0xb000
	ds_read_b128 v[150:153], v106 offset:4096
	ds_read_b128 v[154:157], v106 offset:6144
	v_mfma_f32_16x16x32_bf16 v[34:37], v[82:85], v[54:57], v[34:37]
	global_load_lds_dwordx4 v101, s[0:1]
	v_mfma_f32_16x16x32_bf16 v[30:33], v[66:69], v[58:61], v[30:33]
	s_add_u32 m0, s8, 0xc000
	v_mfma_f32_16x16x32_bf16 v[26:29], v[70:73], v[58:61], v[26:29]
	global_load_lds_dwordx4 v102, s[4:5]
	v_mfma_f32_16x16x32_bf16 v[22:25], v[78:81], v[58:61], v[22:25]
	s_add_u32 m0, s8, 0xd000
	v_mfma_f32_16x16x32_bf16 v[18:21], v[82:85], v[58:61], v[18:21]
	global_load_lds_dwordx4 v103, s[4:5]
	v_mfma_f32_16x16x32_bf16 v[14:17], v[66:69], v[62:65], v[14:17]
	s_add_u32 m0, s8, 0xe000
	v_mfma_f32_16x16x32_bf16 v[10:13], v[70:73], v[62:65], v[10:13]
	global_load_lds_dwordx4 v104, s[4:5]
	v_mfma_f32_16x16x32_bf16 v[2:5], v[78:81], v[62:65], v[2:5]
	s_add_u32 m0, s8, 0xf000
	v_mfma_f32_16x16x32_bf16 v[6:9], v[82:85], v[62:65], v[6:9]
	global_load_lds_dwordx4 v105, s[4:5]
	s_add_u32 s0, s0, 0x80
	s_addc_u32 s1, s1, 0
	s_add_u32 s4, s4, 0x80
	s_addc_u32 s5, s5, 0
	s_waitcnt lgkmcnt(0)
	v_mfma_f32_16x16x32_bf16 v[94:97], v[158:161], v[142:145], v[94:97]
	ds_read_b128 v[50:53], v107
	ds_read_b128 v[66:69], v109 offset:16384
	v_mfma_f32_16x16x32_bf16 v[90:93], v[182:185], v[142:145], v[90:93]
	v_mfma_f32_16x16x32_bf16 v[86:89], v[186:189], v[142:145], v[86:89]
	ds_read_b128 v[70:73], v109 offset:18432
	ds_read_b128 v[78:81], v109 offset:20480
	v_mfma_f32_16x16x32_bf16 v[74:77], v[206:209], v[142:145], v[74:77]
	v_mfma_f32_16x16x32_bf16 v[46:49], v[158:161], v[146:149], v[46:49]
	ds_read_b128 v[82:85], v109 offset:22528
	ds_read_b128 v[54:57], v107 offset:2048
	v_mfma_f32_16x16x32_bf16 v[42:45], v[182:185], v[146:149], v[42:45]
	v_mfma_f32_16x16x32_bf16 v[38:41], v[186:189], v[146:149], v[38:41]
	ds_read_b128 v[58:61], v107 offset:4096
	ds_read_b128 v[62:65], v107 offset:6144
	v_mfma_f32_16x16x32_bf16 v[34:37], v[206:209], v[146:149], v[34:37]
	v_mfma_f32_16x16x32_bf16 v[30:33], v[158:161], v[150:153], v[30:33]
	v_mfma_f32_16x16x32_bf16 v[26:29], v[182:185], v[150:153], v[26:29]
	v_mfma_f32_16x16x32_bf16 v[22:25], v[186:189], v[150:153], v[22:25]
	v_mfma_f32_16x16x32_bf16 v[18:21], v[206:209], v[150:153], v[18:21]
	v_mfma_f32_16x16x32_bf16 v[14:17], v[158:161], v[154:157], v[14:17]
	v_mfma_f32_16x16x32_bf16 v[10:13], v[182:185], v[154:157], v[10:13]
	v_mfma_f32_16x16x32_bf16 v[2:5], v[186:189], v[154:157], v[2:5]
	v_mfma_f32_16x16x32_bf16 v[6:9], v[206:209], v[154:157], v[6:9]
	s_add_i32 s9, s9, -1
	s_waitcnt vmcnt(0) lgkmcnt(0)
	s_barrier
	s_cmp_lg_u32 s9, 0
	s_cbranch_scc1 .Lg1_loop
	v_mfma_f32_16x16x32_bf16 v[94:97], v[66:69], v[50:53], v[94:97]
	ds_read_b128 v[142:145], v106 offset:32768
	ds_read_b128 v[158:161], v108 offset:49152
	v_mfma_f32_16x16x32_bf16 v[90:93], v[70:73], v[50:53], v[90:93]
	v_mfma_f32_16x16x32_bf16 v[86:89], v[78:81], v[50:53], v[86:89]
	ds_read_b128 v[182:185], v108 offset:51200
	ds_read_b128 v[186:189], v108 offset:53248
	v_mfma_f32_16x16x32_bf16 v[74:77], v[82:85], v[50:53], v[74:77]
	v_mfma_f32_16x16x32_bf16 v[46:49], v[66:69], v[54:57], v[46:49]
	ds_read_b128 v[206:209], v108 offset:55296
	ds_read_b128 v[146:149], v106 offset:34816
	v_mfma_f32_16x16x32_bf16 v[42:45], v[70:73], v[54:57], v[42:45]
	v_mfma_f32_16x16x32_bf16 v[38:41], v[78:81], v[54:57], v[38:41]
	ds_read_b128 v[150:153], v106 offset:36864
	ds_read_b128 v[154:157], v106 offset:38912
	v_mfma_f32_16x16x32_bf16 v[34:37], v[82:85], v[54:57], v[34:37]
	v_mfma_f32_16x16x32_bf16 v[30:33], v[66:69], v[58:61], v[30:33]
	v_mfma_f32_16x16x32_bf16 v[26:29], v[70:73], v[58:61], v[26:29]
	v_mfma_f32_16x16x32_bf16 v[22:25], v[78:81], v[58:61], v[22:25]
	v_mfma_f32_16x16x32_bf16 v[18:21], v[82:85], v[58:61], v[18:21]
	v_mfma_f32_16x16x32_bf16 v[14:17], v[66:69], v[62:65], v[14:17]
	v_mfma_f32_16x16x32_bf16 v[10:13], v[70:73], v[62:65], v[10:13]
	v_mfma_f32_16x16x32_bf16 v[2:5], v[78:81], v[62:65], v[2:5]
	v_mfma_f32_16x16x32_bf16 v[6:9], v[82:85], v[62:65], v[6:9]
	s_waitcnt lgkmcnt(0)
	v_mfma_f32_16x16x32_bf16 v[94:97], v[158:161], v[142:145], v[94:97]
	ds_read_b128 v[50:53], v107 offset:32768
	ds_read_b128 v[66:69], v109 offset:49152
	v_mfma_f32_16x16x32_bf16 v[90:93], v[182:185], v[142:145], v[90:93]
	v_mfma_f32_16x16x32_bf16 v[86:89], v[186:189], v[142:145], v[86:89]
	ds_read_b128 v[70:73], v109 offset:51200
	ds_read_b128 v[78:81], v109 offset:53248
	v_mfma_f32_16x16x32_bf16 v[74:77], v[206:209], v[142:145], v[74:77]
	v_mfma_f32_16x16x32_bf16 v[46:49], v[158:161], v[146:149], v[46:49]
	ds_read_b128 v[82:85], v109 offset:55296
	ds_read_b128 v[54:57], v107 offset:34816
	v_mfma_f32_16x16x32_bf16 v[42:45], v[182:185], v[146:149], v[42:45]
	v_mfma_f32_16x16x32_bf16 v[38:41], v[186:189], v[146:149], v[38:41]
	ds_read_b128 v[58:61], v107 offset:36864
	ds_read_b128 v[62:65], v107 offset:38912
	v_mfma_f32_16x16x32_bf16 v[34:37], v[206:209], v[146:149], v[34:37]
	v_mfma_f32_16x16x32_bf16 v[30:33], v[158:161], v[150:153], v[30:33]
	v_mfma_f32_16x16x32_bf16 v[26:29], v[182:185], v[150:153], v[26:29]
	v_mfma_f32_16x16x32_bf16 v[22:25], v[186:189], v[150:153], v[22:25]
	v_mfma_f32_16x16x32_bf16 v[18:21], v[206:209], v[150:153], v[18:21]
	v_mfma_f32_16x16x32_bf16 v[14:17], v[158:161], v[154:157], v[14:17]
	v_mfma_f32_16x16x32_bf16 v[10:13], v[182:185], v[154:157], v[10:13]
	v_mfma_f32_16x16x32_bf16 v[2:5], v[186:189], v[154:157], v[2:5]
	v_mfma_f32_16x16x32_bf16 v[6:9], v[206:209], v[154:157], v[6:9]
	s_waitcnt lgkmcnt(0)
	s_barrier
	v_mfma_f32_16x16x32_bf16 v[94:97], v[66:69], v[50:53], v[94:97]
	v_mfma_f32_16x16x32_bf16 v[90:93], v[70:73], v[50:53], v[90:93]
	v_mfma_f32_16x16x32_bf16 v[86:89], v[78:81], v[50:53], v[86:89]
	v_mfma_f32_16x16x32_bf16 v[74:77], v[82:85], v[50:53], v[74:77]
	v_mfma_f32_16x16x32_bf16 v[46:49], v[66:69], v[54:57], v[46:49]
	v_mfma_f32_16x16x32_bf16 v[42:45], v[70:73], v[54:57], v[42:45]
	v_mfma_f32_16x16x32_bf16 v[38:41], v[78:81], v[54:57], v[38:41]
	v_mfma_f32_16x16x32_bf16 v[34:37], v[82:85], v[54:57], v[34:37]
	v_mfma_f32_16x16x32_bf16 v[30:33], v[66:69], v[58:61], v[30:33]
	v_mfma_f32_16x16x32_bf16 v[26:29], v[70:73], v[58:61], v[26:29]
	v_mfma_f32_16x16x32_bf16 v[22:25], v[78:81], v[58:61], v[22:25]
	v_mfma_f32_16x16x32_bf16 v[18:21], v[82:85], v[58:61], v[18:21]
	v_mfma_f32_16x16x32_bf16 v[14:17], v[66:69], v[62:65], v[14:17]
	v_mfma_f32_16x16x32_bf16 v[10:13], v[70:73], v[62:65], v[10:13]
	v_mfma_f32_16x16x32_bf16 v[2:5], v[78:81], v[62:65], v[2:5]
	v_mfma_f32_16x16x32_bf16 v[6:9], v[82:85], v[62:65], v[6:9]
	s_nop 7
	s_nop 2
